# in-proj epilogue: nontemporal (nt) stores for the PROJ output so A/B tiles stay in L2 (on top of combine fix + rss hoist)
# baseline (speedup 1.0000x reference)
;     __device__ __forceinline__ void operator()(const f32x4 (&acc)[2][2][4][2], const Unit& u, int wr, int wc, int fr, int fq, PG8_LAS unsigned char* lds) const {
;     ...
;                 const int row = u.pm * BM + ai * HALF + wr * 64 + m * 16 + fr; const int t = row & tmask;
;                 const float rs = __builtin_amdgcn_rsqf((float)rss[row] * (2.3283064365386963e-10f / 1024.0f) + 1e-6f);
;                 f32x4 v[2][2];
; #pragma unroll
;                 for (int bj = 0; bj < 2; ++bj)
; #pragma unroll
;                     for (int n = 0; n < 2; ++n) v[bj][n] = acc[ai][bj][m][n] * rs;
;                 if (type <= 1) {
;                     float ss = 0.f;
; #pragma unroll
;                     for (int bj = 0; bj < 2; ++bj)
; #pragma unroll
;                         for (int n = 0; n < 2; ++n) { const f32x4 x = v[bj][n]; ss += (x[0] * x[0] + x[1] * x[1]) + (x[2] * x[2] + x[3] * x[3]); }
;                     ss += __shfl_xor(ss, 16); ss += __shfl_xor(ss, 32);
;                     float rn = __builtin_amdgcn_rsqf(ss * (1.0f / 64.0f) + 1e-6f); if (type == 0) rn *= QSCALE;
; #pragma unroll
;                     for (int bj = 0; bj < 2; ++bj) { const float pf = (float)(bj == 0 ? (t >> 6) : (t & 63)); f32x4 c, s;
; #pragma unroll
;                         for (int e = 0; e < 4; ++e) { const float a = __builtin_amdgcn_fractf(pf * f4[0][e]); c[e] = __builtin_amdgcn_cosf(a); s[e] = __builtin_amdgcn_sinf(a); }
;                         const f32x4 x1 = v[bj][0] * g[bj][0] * rn, x2 = v[bj][1] * g[bj][1] * rn;
;                         v[bj][0] = x1 * c - x2 * s; v[bj][1] = x1 * s + x2 * c; }
;                 } else if (type >= 3) {
;                     const float sc = type == 3 ? QSCALE : 1.0f; const float tf = (float)t;
; #pragma unroll
;                     for (int n = 0; n < 2; ++n) { f32x4 c, s;
; #pragma unroll
;                         for (int e = 0; e < 4; ++e) { const float a = __builtin_amdgcn_fractf(tf * f4[n][e]); c[e] = __builtin_amdgcn_cosf(a) * sc; s[e] = __builtin_amdgcn_sinf(a) * sc; }
;                         const f32x4 x1 = v[0][n], x2 = v[1][n];
;                         v[0][n] = x1 * c - x2 * s; v[1][n] = x1 * s + x2 * c; }
;                     if (type == 4) { float ks = 0.f;
; #pragma unroll
;                         for (int bj = 0; bj < 2; ++bj)
; #pragma unroll
.LBB0_153:
	v_mad_i64_i32 v[136:137], s[12:13], s70, v208, v[190:191]
	v_lshlrev_b64 v[136:137], 7, v[136:137]
	v_lshl_add_u64 v[140:141], v[176:177], 0, v[136:137]
	v_cvt_pk_bf16_f32 v136, v152, v153
	v_cvt_pk_bf16_f32 v137, v154, v155
	v_cvt_pk_bf16_f32 v138, v160, v161
	v_cvt_pk_bf16_f32 v139, v162, v163
	v_add_u32_e32 v152, s45, v194
	v_permlane16_swap_b32_e32 v136, v138
	v_permlane16_swap_b32_e32 v137, v139
	global_store_dwordx4 v[140:141], v[136:139], off nt
	v_ashrrev_i32_e32 v153, 31, v152
	s_andn2_b64 vcc, exec, s[76:77]
	v_cvt_pk_bf16_f32 v136, v156, v157
	v_cvt_pk_bf16_f32 v137, v158, v159
	v_cvt_pk_bf16_f32 v138, v164, v165
	v_cvt_pk_bf16_f32 v139, v166, v167
	v_and_b32_e32 v159, s63, v152
	v_permlane16_swap_b32_e32 v136, v138
	v_permlane16_swap_b32_e32 v137, v139
	global_store_dwordx4 v[140:141], v[136:139], off offset:64 nt
	s_nop 1
	s_waitcnt vmcnt(2)
	v_mov_b64_e32 v[136:137], v[224:225]
	v_ffbh_u32_e32 v138, v137
	v_min_u32_e32 v138, 32, v138
	v_lshlrev_b64 v[136:137], v138, v[136:137]
	v_min_u32_e32 v136, 1, v136
	v_or_b32_e32 v136, v137, v136
	v_cvt_f32_u32_e32 v136, v136
	v_sub_u32_e32 v138, 32, v138
	v_cndmask_b32_e64 v137, 0, 1, s[76:77]
	v_cmp_ne_u32_e64 s[12:13], 1, v137
	v_ldexp_f32 v136, v136, v138
	v_fmamk_f32 v136, v136, 0x2a800000, v204
	v_rsq_f32_e32 v136, v136
	s_mov_b64 s[76:77], -1
	v_pk_mul_f32 v[134:135], v[134:135], v[136:137] op_sel_hi:[1,0]
	v_pk_mul_f32 v[132:133], v[132:133], v[136:137] op_sel_hi:[1,0]
	v_pk_mul_f32 v[130:131], v[130:131], v[136:137] op_sel_hi:[1,0]
	v_pk_mul_f32 v[128:129], v[128:129], v[136:137] op_sel_hi:[1,0]
	v_pk_mul_f32 v[126:127], v[126:127], v[136:137] op_sel_hi:[1,0]
	v_pk_mul_f32 v[124:125], v[124:125], v[136:137] op_sel_hi:[1,0]
	v_pk_mul_f32 v[122:123], v[122:123], v[136:137] op_sel_hi:[1,0]
	v_pk_mul_f32 v[120:121], v[120:121], v[136:137] op_sel_hi:[1,0]
	s_cbranch_vccnz .LBB0_158
	v_mov_b64_e32 v[138:139], v[134:135]
	v_mov_b64_e32 v[146:147], v[130:131]
	v_mov_b64_e32 v[142:143], v[126:127]
	v_mov_b64_e32 v[150:151], v[122:123]
	s_and_b64 vcc, exec, s[10:11]
	v_mov_b32_e32 v158, v213
	v_mov_b64_e32 v[136:137], v[132:133]
	v_mov_b64_e32 v[144:145], v[128:129]
	v_mov_b64_e32 v[140:141], v[124:125]
	v_mov_b64_e32 v[148:149], v[120:121]
	s_cbranch_vccnz .LBB0_157
	v_cvt_f32_u32_e32 v149, v159
	s_andn2_b64 vcc, exec, s[74:75]
	v_mov_b32_e32 v158, v213
	v_mul_f32_e32 v140, v30, v149
	v_fract_f32_e32 v141, v140
	v_mul_f32_e32 v136, v28, v149
	v_mul_f32_e32 v137, v29, v149
	v_cos_f32_e32 v140, v141
	v_sin_f32_e32 v142, v141
	v_mul_f32_e32 v141, v31, v149
	v_fract_f32_e32 v138, v136
	v_fract_f32_e32 v139, v137
	v_fract_f32_e32 v143, v141
	v_cos_f32_e32 v136, v138
	v_sin_f32_e32 v138, v138
	v_cos_f32_e32 v137, v139
	v_cos_f32_e32 v141, v143
	v_sin_f32_e32 v143, v143
	v_sin_f32_e32 v139, v139
	v_pk_mul_f32 v[144:145], v[188:189], v[136:137] op_sel_hi:[0,1]
	v_pk_mul_f32 v[140:141], v[188:189], v[140:141] op_sel_hi:[0,1]
	v_pk_mul_f32 v[142:143], v[188:189], v[142:143] op_sel_hi:[0,1]
	v_pk_mul_f32 v[146:147], v[188:189], v[138:139] op_sel_hi:[0,1]
	v_pk_mul_f32 v[136:137], v[146:147], v[124:125]
	v_pk_mul_f32 v[138:139], v[142:143], v[126:127]
	v_pk_fma_f32 v[136:137], v[144:145], v[132:133], v[136:137] neg_lo:[0,0,1] neg_hi:[0,0,1]
	v_pk_fma_f32 v[138:139], v[140:141], v[134:135], v[138:139] neg_lo:[0,0,1] neg_hi:[0,0,1]
	v_pk_mul_f32 v[144:145], v[144:145], v[124:125]
	v_pk_mul_f32 v[140:141], v[140:141], v[126:127]
	v_mul_f32_e32 v148, v54, v149
	v_pk_fma_f32 v[142:143], v[142:143], v[134:135], v[140:141]
	v_pk_fma_f32 v[140:141], v[146:147], v[132:133], v[144:145]
	v_mul_f32_e32 v144, v52, v149
	v_fract_f32_e32 v145, v144
	v_cos_f32_e32 v144, v145
	v_sin_f32_e32 v146, v145
	v_mul_f32_e32 v145, v53, v149
	v_mul_f32_e32 v149, v55, v149
	v_fract_f32_e32 v147, v145
	v_fract_f32_e32 v150, v148
	v_fract_f32_e32 v151, v149
	v_cos_f32_e32 v145, v147
	v_cos_f32_e32 v148, v150
	v_sin_f32_e32 v150, v150
	v_cos_f32_e32 v149, v151
	v_sin_f32_e32 v151, v151
	v_sin_f32_e32 v147, v147
	v_pk_mul_f32 v[154:155], v[188:189], v[144:145] op_sel_hi:[0,1]
	v_pk_mul_f32 v[148:149], v[188:189], v[148:149] op_sel_hi:[0,1]
	v_pk_mul_f32 v[150:151], v[188:189], v[150:151] op_sel_hi:[0,1]
	v_pk_mul_f32 v[156:157], v[188:189], v[146:147] op_sel_hi:[0,1]
	v_pk_mul_f32 v[144:145], v[156:157], v[120:121]
	v_pk_mul_f32 v[146:147], v[150:151], v[122:123]
	v_pk_fma_f32 v[144:145], v[154:155], v[128:129], v[144:145] neg_lo:[0,0,1] neg_hi:[0,0,1]
	v_pk_fma_f32 v[146:147], v[148:149], v[130:131], v[146:147] neg_lo:[0,0,1] neg_hi:[0,0,1]
	v_pk_mul_f32 v[154:155], v[154:155], v[120:121]
	v_pk_mul_f32 v[148:149], v[148:149], v[122:123]
	s_nop 0
	v_pk_fma_f32 v[150:151], v[150:151], v[130:131], v[148:149]
	v_pk_fma_f32 v[148:149], v[156:157], v[128:129], v[154:155]
	s_cbranch_vccnz .LBB0_157
	v_pk_mul_f32 v[154:155], v[138:139], v[138:139]
	v_pk_mul_f32 v[156:157], v[136:137], v[136:137]
	s_nop 0
	v_pk_mov_b32 v[160:161], v[156:157], v[154:155] op_sel:[1,0]
	v_mov_b32_e32 v157, v155
	v_pk_add_f32 v[154:155], v[160:161], v[156:157]
	v_pk_mul_f32 v[156:157], v[146:147], v[146:147]
	v_pk_add_f32 v[154:155], v[154:155], v[154:155] op_sel_hi:[0,1]
	v_pk_mul_f32 v[160:161], v[144:145], v[144:145]
	v_mul_f32_e32 v154, v140, v140
	v_pk_mov_b32 v[162:163], v[160:161], v[156:157] op_sel:[1,0]
	v_mov_b32_e32 v161, v157
	v_pk_add_f32 v[156:157], v[162:163], v[160:161]
	v_pk_fma_f32 v[160:161], v[140:141], v[140:141], v[154:155] op_sel_hi:[1,1,0]
	v_mul_f32_e32 v154, v142, v142
	v_pk_add_f32 v[156:157], v[156:157], v[156:157] op_sel_hi:[0,1]
	v_pk_fma_f32 v[162:163], v[142:143], v[142:143], v[154:155] op_sel_hi:[1,1,0]
	v_mul_f32_e32 v160, v148, v148
	v_mul_f32_e32 v162, v149, v149
	v_mul_f32_e32 v154, v150, v150
	v_mul_f32_e32 v156, v151, v151
	v_pk_add_f32 v[160:161], v[160:161], v[162:163]
	v_pk_add_f32 v[154:155], v[154:155], v[156:157]
	v_and_b32_e32 v156, 64, v207
	v_pk_add_f32 v[154:155], v[160:161], v[154:155]
	v_add_u32_e32 v156, 64, v156
	v_add_f32_e32 v154, v154, v155
	v_xor_b32_e32 v155, 16, v207
	v_cmp_lt_i32_e32 vcc, v155, v156
	s_nop 1
	v_cndmask_b32_e32 v155, v207, v155, vcc
	v_lshlrev_b32_e32 v155, 2, v155
	ds_bpermute_b32 v155, v155, v154
	s_waitcnt lgkmcnt(0)
	v_add_f32_e32 v154, v154, v155
	v_xor_b32_e32 v155, 32, v207
	v_cmp_lt_i32_e32 vcc, v155, v156
	s_nop 1
	v_cndmask_b32_e32 v155, v207, v155, vcc
	v_lshlrev_b32_e32 v155, 2, v155
	ds_bpermute_b32 v155, v155, v154
	s_waitcnt lgkmcnt(0)
	v_add_f32_e32 v154, v154, v155
	v_max_f32_e32 v155, v213, v213
	v_max_f32_e32 v158, v155, v154

;     __device__ __forceinline__ void operator()(const f32x4 (&acc)[2][2][4][2], const Unit& u, int wr, int wc, int fr, int fq, PG8_LAS unsigned char* lds) const {
;     ...
;                 const int row = u.pm * BM + ai * HALF + wr * 64 + m * 16 + fr; const int t = row & tmask;
;                 const float rs = __builtin_amdgcn_rsqf((float)rss[row] * (2.3283064365386963e-10f / 1024.0f) + 1e-6f);
;                 f32x4 v[2][2];
; #pragma unroll
;                 for (int bj = 0; bj < 2; ++bj)
; #pragma unroll
;                     for (int n = 0; n < 2; ++n) v[bj][n] = acc[ai][bj][m][n] * rs;
;                 if (type <= 1) {
;                     float ss = 0.f;
; #pragma unroll
;                     for (int bj = 0; bj < 2; ++bj)
; #pragma unroll
;                         for (int n = 0; n < 2; ++n) { const f32x4 x = v[bj][n]; ss += (x[0] * x[0] + x[1] * x[1]) + (x[2] * x[2] + x[3] * x[3]); }
;                     ss += __shfl_xor(ss, 16); ss += __shfl_xor(ss, 32);
;                     float rn = __builtin_amdgcn_rsqf(ss * (1.0f / 64.0f) + 1e-6f); if (type == 0) rn *= QSCALE;
; #pragma unroll
;                     for (int bj = 0; bj < 2; ++bj) { const float pf = (float)(bj == 0 ? (t >> 6) : (t & 63)); f32x4 c, s;
; #pragma unroll
;                         for (int e = 0; e < 4; ++e) { const float a = __builtin_amdgcn_fractf(pf * f4[0][e]); c[e] = __builtin_amdgcn_cosf(a); s[e] = __builtin_amdgcn_sinf(a); }
;                         const f32x4 x1 = v[bj][0] * g[bj][0] * rn, x2 = v[bj][1] * g[bj][1] * rn;
;                         v[bj][0] = x1 * c - x2 * s; v[bj][1] = x1 * s + x2 * c; }
;                 } else if (type >= 3) {
;                     const float sc = type == 3 ? QSCALE : 1.0f; const float tf = (float)t;
; #pragma unroll
;                     for (int n = 0; n < 2; ++n) { f32x4 c, s;
; #pragma unroll
;                         for (int e = 0; e < 4; ++e) { const float a = __builtin_amdgcn_fractf(tf * f4[n][e]); c[e] = __builtin_amdgcn_cosf(a) * sc; s[e] = __builtin_amdgcn_sinf(a) * sc; }
;                         const f32x4 x1 = v[0][n], x2 = v[1][n];
;                         v[0][n] = x1 * c - x2 * s; v[1][n] = x1 * s + x2 * c; }
;                     if (type == 4) { float ks = 0.f;
; #pragma unroll
;                         for (int bj = 0; bj < 2; ++bj)
; #pragma unroll
.LBB0_160:
	s_mul_hi_i32 s77, s70, 0x14000
	s_mul_i32 s76, s70, 0x14000
	v_lshl_add_u64 v[120:121], s[76:77], 0, v[152:153]
	v_lshlrev_b64 v[120:121], 7, v[120:121]
	v_lshl_add_u64 v[124:125], v[176:177], 0, v[120:121]
	v_cvt_pk_bf16_f32 v120, v136, v137
	v_cvt_pk_bf16_f32 v121, v138, v139
	v_cvt_pk_bf16_f32 v122, v144, v145
	v_cvt_pk_bf16_f32 v123, v146, v147
	v_add_u32_e32 v136, s45, v196
	v_permlane16_swap_b32_e32 v120, v122
	v_permlane16_swap_b32_e32 v121, v123
	global_store_dwordx4 v[124:125], v[120:123], off nt
	v_ashrrev_i32_e32 v137, 31, v136
	s_and_b64 vcc, exec, s[12:13]
	v_cvt_pk_bf16_f32 v120, v140, v141
	v_cvt_pk_bf16_f32 v121, v142, v143
	v_cvt_pk_bf16_f32 v122, v148, v149
	v_cvt_pk_bf16_f32 v123, v150, v151
	v_and_b32_e32 v143, s63, v136
	v_permlane16_swap_b32_e32 v120, v122
	v_permlane16_swap_b32_e32 v121, v123
	global_store_dwordx4 v[124:125], v[120:123], off offset:64 nt
	s_mov_b64 s[78:79], -1
	s_nop 0
	s_waitcnt vmcnt(4)
	v_mov_b64_e32 v[120:121], v[226:227]
	v_ffbh_u32_e32 v122, v121
	v_min_u32_e32 v122, 32, v122
	v_lshlrev_b64 v[120:121], v122, v[120:121]
	v_min_u32_e32 v120, 1, v120
	v_or_b32_e32 v120, v121, v120
	v_cvt_f32_u32_e32 v120, v120
	v_sub_u32_e32 v121, 32, v122
	v_ldexp_f32 v120, v120, v121
	v_fmamk_f32 v120, v120, 0x2a800000, v204
	v_rsq_f32_e32 v120, v120
	s_nop 0
	v_pk_mul_f32 v[118:119], v[118:119], v[120:121] op_sel_hi:[1,0]
	v_pk_mul_f32 v[116:117], v[116:117], v[120:121] op_sel_hi:[1,0]
	v_pk_mul_f32 v[114:115], v[114:115], v[120:121] op_sel_hi:[1,0]
	v_pk_mul_f32 v[112:113], v[112:113], v[120:121] op_sel_hi:[1,0]
	v_pk_mul_f32 v[110:111], v[110:111], v[120:121] op_sel_hi:[1,0]
	v_pk_mul_f32 v[108:109], v[108:109], v[120:121] op_sel_hi:[1,0]
	v_pk_mul_f32 v[106:107], v[106:107], v[120:121] op_sel_hi:[1,0]
	v_pk_mul_f32 v[104:105], v[104:105], v[120:121] op_sel_hi:[1,0]
	s_cbranch_vccnz .LBB0_165
	v_mov_b64_e32 v[122:123], v[118:119]
	v_mov_b64_e32 v[130:131], v[114:115]
	v_mov_b64_e32 v[126:127], v[110:111]
	v_mov_b64_e32 v[134:135], v[106:107]
	s_and_b64 vcc, exec, s[10:11]
	v_mov_b32_e32 v142, v158
	v_mov_b64_e32 v[120:121], v[116:117]
	v_mov_b64_e32 v[128:129], v[112:113]
	v_mov_b64_e32 v[124:125], v[108:109]
	v_mov_b64_e32 v[132:133], v[104:105]
	s_cbranch_vccnz .LBB0_164
	v_cvt_f32_u32_e32 v133, v143
	s_andn2_b64 vcc, exec, s[74:75]
	v_mov_b32_e32 v142, v158
	v_mul_f32_e32 v124, v30, v133
	v_fract_f32_e32 v125, v124
	v_mul_f32_e32 v120, v28, v133
	v_mul_f32_e32 v121, v29, v133
	v_cos_f32_e32 v124, v125
	v_sin_f32_e32 v126, v125
	v_mul_f32_e32 v125, v31, v133
	v_fract_f32_e32 v122, v120
	v_fract_f32_e32 v123, v121
	v_fract_f32_e32 v127, v125
	v_cos_f32_e32 v120, v122
	v_sin_f32_e32 v122, v122
	v_cos_f32_e32 v121, v123
	v_cos_f32_e32 v125, v127
	v_sin_f32_e32 v127, v127
	v_sin_f32_e32 v123, v123
	v_pk_mul_f32 v[128:129], v[188:189], v[120:121] op_sel_hi:[0,1]
	v_pk_mul_f32 v[124:125], v[188:189], v[124:125] op_sel_hi:[0,1]
	v_pk_mul_f32 v[126:127], v[188:189], v[126:127] op_sel_hi:[0,1]
	v_pk_mul_f32 v[130:131], v[188:189], v[122:123] op_sel_hi:[0,1]
	v_pk_mul_f32 v[120:121], v[130:131], v[108:109]
	v_pk_mul_f32 v[122:123], v[126:127], v[110:111]
	v_pk_fma_f32 v[120:121], v[128:129], v[116:117], v[120:121] neg_lo:[0,0,1] neg_hi:[0,0,1]
	v_pk_fma_f32 v[122:123], v[124:125], v[118:119], v[122:123] neg_lo:[0,0,1] neg_hi:[0,0,1]
	v_pk_mul_f32 v[128:129], v[128:129], v[108:109]
	v_pk_mul_f32 v[124:125], v[124:125], v[110:111]
	v_mul_f32_e32 v132, v54, v133
	v_pk_fma_f32 v[126:127], v[126:127], v[118:119], v[124:125]
	v_pk_fma_f32 v[124:125], v[130:131], v[116:117], v[128:129]
	v_mul_f32_e32 v128, v52, v133
	v_fract_f32_e32 v129, v128
	v_cos_f32_e32 v128, v129
	v_sin_f32_e32 v130, v129
	v_mul_f32_e32 v129, v53, v133
	v_mul_f32_e32 v133, v55, v133
	v_fract_f32_e32 v131, v129
	v_fract_f32_e32 v134, v132
	v_fract_f32_e32 v135, v133
	v_cos_f32_e32 v129, v131
	v_cos_f32_e32 v132, v134
	v_sin_f32_e32 v134, v134
	v_cos_f32_e32 v133, v135
	v_sin_f32_e32 v135, v135
	v_sin_f32_e32 v131, v131
	v_pk_mul_f32 v[138:139], v[188:189], v[128:129] op_sel_hi:[0,1]
	v_pk_mul_f32 v[132:133], v[188:189], v[132:133] op_sel_hi:[0,1]
	v_pk_mul_f32 v[134:135], v[188:189], v[134:135] op_sel_hi:[0,1]
	v_pk_mul_f32 v[140:141], v[188:189], v[130:131] op_sel_hi:[0,1]
	v_pk_mul_f32 v[128:129], v[140:141], v[104:105]
	v_pk_mul_f32 v[130:131], v[134:135], v[106:107]
	v_pk_fma_f32 v[128:129], v[138:139], v[112:113], v[128:129] neg_lo:[0,0,1] neg_hi:[0,0,1]
	v_pk_fma_f32 v[130:131], v[132:133], v[114:115], v[130:131] neg_lo:[0,0,1] neg_hi:[0,0,1]
	v_pk_mul_f32 v[138:139], v[138:139], v[104:105]
	v_pk_mul_f32 v[132:133], v[132:133], v[106:107]
	s_nop 0
	v_pk_fma_f32 v[134:135], v[134:135], v[114:115], v[132:133]
	v_pk_fma_f32 v[132:133], v[140:141], v[112:113], v[138:139]
	s_cbranch_vccnz .LBB0_164
	v_pk_mul_f32 v[138:139], v[122:123], v[122:123]
	v_pk_mul_f32 v[140:141], v[120:121], v[120:121]
	s_nop 0
	v_pk_mov_b32 v[144:145], v[140:141], v[138:139] op_sel:[1,0]
	v_mov_b32_e32 v141, v139
	v_pk_add_f32 v[138:139], v[144:145], v[140:141]
	v_pk_mul_f32 v[140:141], v[130:131], v[130:131]
	v_pk_add_f32 v[138:139], v[138:139], v[138:139] op_sel_hi:[0,1]
	v_pk_mul_f32 v[144:145], v[128:129], v[128:129]
	v_mul_f32_e32 v138, v124, v124
	v_pk_mov_b32 v[146:147], v[144:145], v[140:141] op_sel:[1,0]
	v_mov_b32_e32 v145, v141
	v_pk_add_f32 v[140:141], v[146:147], v[144:145]
	v_pk_fma_f32 v[144:145], v[124:125], v[124:125], v[138:139] op_sel_hi:[1,1,0]
	v_mul_f32_e32 v138, v126, v126
	v_pk_add_f32 v[140:141], v[140:141], v[140:141] op_sel_hi:[0,1]
	v_pk_fma_f32 v[146:147], v[126:127], v[126:127], v[138:139] op_sel_hi:[1,1,0]
	v_mul_f32_e32 v144, v132, v132
	v_mul_f32_e32 v146, v133, v133
	v_mul_f32_e32 v138, v134, v134
	v_mul_f32_e32 v140, v135, v135
	v_pk_add_f32 v[144:145], v[144:145], v[146:147]
	v_pk_add_f32 v[138:139], v[138:139], v[140:141]
	v_and_b32_e32 v140, 64, v207
	v_pk_add_f32 v[138:139], v[144:145], v[138:139]
	v_add_u32_e32 v140, 64, v140
	v_add_f32_e32 v138, v138, v139
	v_xor_b32_e32 v139, 16, v207
	v_cmp_lt_i32_e32 vcc, v139, v140
	s_nop 1
	v_cndmask_b32_e32 v139, v207, v139, vcc
	v_lshlrev_b32_e32 v139, 2, v139
	ds_bpermute_b32 v139, v139, v138
	s_waitcnt lgkmcnt(0)
	v_add_f32_e32 v138, v138, v139
	v_xor_b32_e32 v139, 32, v207
	v_cmp_lt_i32_e32 vcc, v139, v140
	s_nop 1
	v_cndmask_b32_e32 v139, v207, v139, vcc
	v_lshlrev_b32_e32 v139, 2, v139
	ds_bpermute_b32 v139, v139, v138
	s_waitcnt lgkmcnt(0)
	v_add_f32_e32 v138, v138, v139
	v_max_f32_e32 v139, v158, v158
	v_max_f32_e32 v142, v139, v138

;     __device__ __forceinline__ void operator()(const f32x4 (&acc)[2][2][4][2], const Unit& u, int wr, int wc, int fr, int fq, PG8_LAS unsigned char* lds) const {
;     ...
;                 const int row = u.pm * BM + ai * HALF + wr * 64 + m * 16 + fr; const int t = row & tmask;
;                 const float rs = __builtin_amdgcn_rsqf((float)rss[row] * (2.3283064365386963e-10f / 1024.0f) + 1e-6f);
;                 f32x4 v[2][2];
; #pragma unroll
;                 for (int bj = 0; bj < 2; ++bj)
; #pragma unroll
;                     for (int n = 0; n < 2; ++n) v[bj][n] = acc[ai][bj][m][n] * rs;
;                 if (type <= 1) {
;                     float ss = 0.f;
; #pragma unroll
;                     for (int bj = 0; bj < 2; ++bj)
; #pragma unroll
;                         for (int n = 0; n < 2; ++n) { const f32x4 x = v[bj][n]; ss += (x[0] * x[0] + x[1] * x[1]) + (x[2] * x[2] + x[3] * x[3]); }
;                     ss += __shfl_xor(ss, 16); ss += __shfl_xor(ss, 32);
;                     float rn = __builtin_amdgcn_rsqf(ss * (1.0f / 64.0f) + 1e-6f); if (type == 0) rn *= QSCALE;
; #pragma unroll
;                     for (int bj = 0; bj < 2; ++bj) { const float pf = (float)(bj == 0 ? (t >> 6) : (t & 63)); f32x4 c, s;
; #pragma unroll
;                         for (int e = 0; e < 4; ++e) { const float a = __builtin_amdgcn_fractf(pf * f4[0][e]); c[e] = __builtin_amdgcn_cosf(a); s[e] = __builtin_amdgcn_sinf(a); }
;                         const f32x4 x1 = v[bj][0] * g[bj][0] * rn, x2 = v[bj][1] * g[bj][1] * rn;
;                         v[bj][0] = x1 * c - x2 * s; v[bj][1] = x1 * s + x2 * c; }
;                 } else if (type >= 3) {
;                     const float sc = type == 3 ? QSCALE : 1.0f; const float tf = (float)t;
; #pragma unroll
;                     for (int n = 0; n < 2; ++n) { f32x4 c, s;
; #pragma unroll
;                         for (int e = 0; e < 4; ++e) { const float a = __builtin_amdgcn_fractf(tf * f4[n][e]); c[e] = __builtin_amdgcn_cosf(a) * sc; s[e] = __builtin_amdgcn_sinf(a) * sc; }
;                         const f32x4 x1 = v[0][n], x2 = v[1][n];
;                         v[0][n] = x1 * c - x2 * s; v[1][n] = x1 * s + x2 * c; }
;                     if (type == 4) { float ks = 0.f;
; #pragma unroll
;                         for (int bj = 0; bj < 2; ++bj)
; #pragma unroll
.LBB0_167:
	v_lshl_add_u64 v[104:105], s[76:77], 0, v[136:137]
	v_lshlrev_b64 v[104:105], 7, v[104:105]
	v_lshl_add_u64 v[108:109], v[176:177], 0, v[104:105]
	v_cvt_pk_bf16_f32 v104, v120, v121
	v_cvt_pk_bf16_f32 v105, v122, v123
	v_cvt_pk_bf16_f32 v106, v128, v129
	v_cvt_pk_bf16_f32 v107, v130, v131
	v_add_u32_e32 v120, s45, v198
	v_permlane16_swap_b32_e32 v104, v106
	v_permlane16_swap_b32_e32 v105, v107
	global_store_dwordx4 v[108:109], v[104:107], off nt
	v_ashrrev_i32_e32 v121, 31, v120
	s_and_b64 vcc, exec, s[12:13]
	v_cvt_pk_bf16_f32 v104, v124, v125
	v_cvt_pk_bf16_f32 v105, v126, v127
	v_cvt_pk_bf16_f32 v106, v132, v133
	v_cvt_pk_bf16_f32 v107, v134, v135
	v_and_b32_e32 v127, s63, v120
	v_permlane16_swap_b32_e32 v104, v106
	v_permlane16_swap_b32_e32 v105, v107
	global_store_dwordx4 v[108:109], v[104:107], off offset:64 nt
	s_mov_b64 s[78:79], -1
	s_nop 0
	s_waitcnt vmcnt(6)
	v_mov_b64_e32 v[104:105], v[228:229]
	v_ffbh_u32_e32 v106, v105
	v_min_u32_e32 v106, 32, v106
	v_lshlrev_b64 v[104:105], v106, v[104:105]
	v_min_u32_e32 v104, 1, v104
	v_or_b32_e32 v104, v105, v104
	v_cvt_f32_u32_e32 v104, v104
	v_sub_u32_e32 v105, 32, v106
	v_ldexp_f32 v104, v104, v105
	v_fmamk_f32 v104, v104, 0x2a800000, v204
	v_rsq_f32_e32 v104, v104
	s_nop 0
	v_pk_mul_f32 v[102:103], v[102:103], v[104:105] op_sel_hi:[1,0]
	v_pk_mul_f32 v[100:101], v[100:101], v[104:105] op_sel_hi:[1,0]
	v_pk_mul_f32 v[98:99], v[98:99], v[104:105] op_sel_hi:[1,0]
	v_pk_mul_f32 v[96:97], v[96:97], v[104:105] op_sel_hi:[1,0]
	v_pk_mul_f32 v[94:95], v[94:95], v[104:105] op_sel_hi:[1,0]
	v_pk_mul_f32 v[92:93], v[92:93], v[104:105] op_sel_hi:[1,0]
	v_pk_mul_f32 v[90:91], v[90:91], v[104:105] op_sel_hi:[1,0]
	v_pk_mul_f32 v[88:89], v[88:89], v[104:105] op_sel_hi:[1,0]
	s_cbranch_vccnz .LBB0_172
	v_mov_b64_e32 v[106:107], v[102:103]
	v_mov_b64_e32 v[114:115], v[98:99]
	v_mov_b64_e32 v[110:111], v[94:95]
	v_mov_b64_e32 v[118:119], v[90:91]
	s_and_b64 vcc, exec, s[10:11]
	v_mov_b32_e32 v126, v142
	v_mov_b64_e32 v[104:105], v[100:101]
	v_mov_b64_e32 v[112:113], v[96:97]
	v_mov_b64_e32 v[108:109], v[92:93]
	v_mov_b64_e32 v[116:117], v[88:89]
	s_cbranch_vccnz .LBB0_171
	v_cvt_f32_u32_e32 v117, v127
	s_andn2_b64 vcc, exec, s[74:75]
	v_mov_b32_e32 v126, v142
	v_mul_f32_e32 v108, v30, v117
	v_fract_f32_e32 v109, v108
	v_mul_f32_e32 v104, v28, v117
	v_mul_f32_e32 v105, v29, v117
	v_cos_f32_e32 v108, v109
	v_sin_f32_e32 v110, v109
	v_mul_f32_e32 v109, v31, v117
	v_fract_f32_e32 v106, v104
	v_fract_f32_e32 v107, v105
	v_fract_f32_e32 v111, v109
	v_cos_f32_e32 v104, v106
	v_sin_f32_e32 v106, v106
	v_cos_f32_e32 v105, v107
	v_cos_f32_e32 v109, v111
	v_sin_f32_e32 v111, v111
	v_sin_f32_e32 v107, v107
	v_pk_mul_f32 v[112:113], v[188:189], v[104:105] op_sel_hi:[0,1]
	v_pk_mul_f32 v[108:109], v[188:189], v[108:109] op_sel_hi:[0,1]
	v_pk_mul_f32 v[110:111], v[188:189], v[110:111] op_sel_hi:[0,1]
	v_pk_mul_f32 v[114:115], v[188:189], v[106:107] op_sel_hi:[0,1]
	v_pk_mul_f32 v[104:105], v[114:115], v[92:93]
	v_pk_mul_f32 v[106:107], v[110:111], v[94:95]
	v_pk_fma_f32 v[104:105], v[112:113], v[100:101], v[104:105] neg_lo:[0,0,1] neg_hi:[0,0,1]
	v_pk_fma_f32 v[106:107], v[108:109], v[102:103], v[106:107] neg_lo:[0,0,1] neg_hi:[0,0,1]
	v_pk_mul_f32 v[112:113], v[112:113], v[92:93]
	v_pk_mul_f32 v[108:109], v[108:109], v[94:95]
	v_mul_f32_e32 v116, v54, v117
	v_pk_fma_f32 v[110:111], v[110:111], v[102:103], v[108:109]
	v_pk_fma_f32 v[108:109], v[114:115], v[100:101], v[112:113]
	v_mul_f32_e32 v112, v52, v117
	v_fract_f32_e32 v113, v112
	v_cos_f32_e32 v112, v113
	v_sin_f32_e32 v114, v113
	v_mul_f32_e32 v113, v53, v117
	v_mul_f32_e32 v117, v55, v117
	v_fract_f32_e32 v115, v113
	v_fract_f32_e32 v118, v116
	v_fract_f32_e32 v119, v117
	v_cos_f32_e32 v113, v115
	v_cos_f32_e32 v116, v118
	v_sin_f32_e32 v118, v118
	v_cos_f32_e32 v117, v119
	v_sin_f32_e32 v119, v119
	v_sin_f32_e32 v115, v115
	v_pk_mul_f32 v[122:123], v[188:189], v[112:113] op_sel_hi:[0,1]
	v_pk_mul_f32 v[116:117], v[188:189], v[116:117] op_sel_hi:[0,1]
	v_pk_mul_f32 v[118:119], v[188:189], v[118:119] op_sel_hi:[0,1]
	v_pk_mul_f32 v[124:125], v[188:189], v[114:115] op_sel_hi:[0,1]
	v_pk_mul_f32 v[112:113], v[124:125], v[88:89]
	v_pk_mul_f32 v[114:115], v[118:119], v[90:91]
	v_pk_fma_f32 v[112:113], v[122:123], v[96:97], v[112:113] neg_lo:[0,0,1] neg_hi:[0,0,1]
	v_pk_fma_f32 v[114:115], v[116:117], v[98:99], v[114:115] neg_lo:[0,0,1] neg_hi:[0,0,1]
	v_pk_mul_f32 v[122:123], v[122:123], v[88:89]
	v_pk_mul_f32 v[116:117], v[116:117], v[90:91]
	s_nop 0
	v_pk_fma_f32 v[118:119], v[118:119], v[98:99], v[116:117]
	v_pk_fma_f32 v[116:117], v[124:125], v[96:97], v[122:123]
	s_cbranch_vccnz .LBB0_171
	v_pk_mul_f32 v[122:123], v[106:107], v[106:107]
	v_pk_mul_f32 v[124:125], v[104:105], v[104:105]
	s_nop 0
	v_pk_mov_b32 v[128:129], v[124:125], v[122:123] op_sel:[1,0]
	v_mov_b32_e32 v125, v123
	v_pk_add_f32 v[122:123], v[128:129], v[124:125]
	v_pk_mul_f32 v[124:125], v[114:115], v[114:115]
	v_pk_add_f32 v[122:123], v[122:123], v[122:123] op_sel_hi:[0,1]
	v_pk_mul_f32 v[128:129], v[112:113], v[112:113]
	v_mul_f32_e32 v122, v108, v108
	v_pk_mov_b32 v[130:131], v[128:129], v[124:125] op_sel:[1,0]
	v_mov_b32_e32 v129, v125
	v_pk_add_f32 v[124:125], v[130:131], v[128:129]
	v_pk_fma_f32 v[128:129], v[108:109], v[108:109], v[122:123] op_sel_hi:[1,1,0]
	v_mul_f32_e32 v122, v110, v110
	v_pk_add_f32 v[124:125], v[124:125], v[124:125] op_sel_hi:[0,1]
	v_pk_fma_f32 v[130:131], v[110:111], v[110:111], v[122:123] op_sel_hi:[1,1,0]
	v_mul_f32_e32 v128, v116, v116
	v_mul_f32_e32 v130, v117, v117
	v_mul_f32_e32 v122, v118, v118
	v_mul_f32_e32 v124, v119, v119
	v_pk_add_f32 v[128:129], v[128:129], v[130:131]
	v_pk_add_f32 v[122:123], v[122:123], v[124:125]
	v_and_b32_e32 v124, 64, v207
	v_pk_add_f32 v[122:123], v[128:129], v[122:123]
	v_add_u32_e32 v124, 64, v124
	v_add_f32_e32 v122, v122, v123
	v_xor_b32_e32 v123, 16, v207
	v_cmp_lt_i32_e32 vcc, v123, v124
	s_nop 1
	v_cndmask_b32_e32 v123, v207, v123, vcc
	v_lshlrev_b32_e32 v123, 2, v123
	ds_bpermute_b32 v123, v123, v122
	s_waitcnt lgkmcnt(0)
	v_add_f32_e32 v122, v122, v123
	v_xor_b32_e32 v123, 32, v207
	v_cmp_lt_i32_e32 vcc, v123, v124
	s_nop 1
	v_cndmask_b32_e32 v123, v207, v123, vcc
	v_lshlrev_b32_e32 v123, 2, v123
	ds_bpermute_b32 v123, v123, v122
	s_waitcnt lgkmcnt(0)
	v_add_f32_e32 v122, v122, v123
	v_max_f32_e32 v123, v142, v142
	v_max_f32_e32 v126, v123, v122

;     __device__ __forceinline__ void operator()(const f32x4 (&acc)[2][2][4][2], const Unit& u, int wr, int wc, int fr, int fq, PG8_LAS unsigned char* lds) const {
;     ...
;                 const int row = u.pm * BM + ai * HALF + wr * 64 + m * 16 + fr; const int t = row & tmask;
;                 const float rs = __builtin_amdgcn_rsqf((float)rss[row] * (2.3283064365386963e-10f / 1024.0f) + 1e-6f);
;                 f32x4 v[2][2];
; #pragma unroll
;                 for (int bj = 0; bj < 2; ++bj)
; #pragma unroll
;                     for (int n = 0; n < 2; ++n) v[bj][n] = acc[ai][bj][m][n] * rs;
;                 if (type <= 1) {
;                     float ss = 0.f;
; #pragma unroll
;                     for (int bj = 0; bj < 2; ++bj)
; #pragma unroll
;                         for (int n = 0; n < 2; ++n) { const f32x4 x = v[bj][n]; ss += (x[0] * x[0] + x[1] * x[1]) + (x[2] * x[2] + x[3] * x[3]); }
;                     ss += __shfl_xor(ss, 16); ss += __shfl_xor(ss, 32);
;                     float rn = __builtin_amdgcn_rsqf(ss * (1.0f / 64.0f) + 1e-6f); if (type == 0) rn *= QSCALE;
; #pragma unroll
;                     for (int bj = 0; bj < 2; ++bj) { const float pf = (float)(bj == 0 ? (t >> 6) : (t & 63)); f32x4 c, s;
; #pragma unroll
;                         for (int e = 0; e < 4; ++e) { const float a = __builtin_amdgcn_fractf(pf * f4[0][e]); c[e] = __builtin_amdgcn_cosf(a); s[e] = __builtin_amdgcn_sinf(a); }
;                         const f32x4 x1 = v[bj][0] * g[bj][0] * rn, x2 = v[bj][1] * g[bj][1] * rn;
;                         v[bj][0] = x1 * c - x2 * s; v[bj][1] = x1 * s + x2 * c; }
;                 } else if (type >= 3) {
;                     const float sc = type == 3 ? QSCALE : 1.0f; const float tf = (float)t;
; #pragma unroll
;                     for (int n = 0; n < 2; ++n) { f32x4 c, s;
; #pragma unroll
;                         for (int e = 0; e < 4; ++e) { const float a = __builtin_amdgcn_fractf(tf * f4[n][e]); c[e] = __builtin_amdgcn_cosf(a) * sc; s[e] = __builtin_amdgcn_sinf(a) * sc; }
;                         const f32x4 x1 = v[0][n], x2 = v[1][n];
;                         v[0][n] = x1 * c - x2 * s; v[1][n] = x1 * s + x2 * c; }
;                     if (type == 4) { float ks = 0.f;
; #pragma unroll
;                         for (int bj = 0; bj < 2; ++bj)
; #pragma unroll
.LBB0_174:
	v_lshl_add_u64 v[88:89], s[76:77], 0, v[120:121]
	v_lshlrev_b64 v[88:89], 7, v[88:89]
	v_lshl_add_u64 v[92:93], v[176:177], 0, v[88:89]
	v_cvt_pk_bf16_f32 v88, v104, v105
	v_cvt_pk_bf16_f32 v89, v106, v107
	v_cvt_pk_bf16_f32 v90, v112, v113
	v_cvt_pk_bf16_f32 v91, v114, v115
	v_add_u32_e32 v104, 0x80, v190
	v_permlane16_swap_b32_e32 v88, v90
	v_permlane16_swap_b32_e32 v89, v91
	global_store_dwordx4 v[92:93], v[88:91], off nt
	v_ashrrev_i32_e32 v105, 31, v104
	s_and_b64 vcc, exec, s[12:13]
	v_cvt_pk_bf16_f32 v88, v108, v109
	v_cvt_pk_bf16_f32 v89, v110, v111
	v_cvt_pk_bf16_f32 v90, v116, v117
	v_cvt_pk_bf16_f32 v91, v118, v119
	v_and_b32_e32 v107, s63, v104
	v_permlane16_swap_b32_e32 v88, v90
	v_permlane16_swap_b32_e32 v89, v91
	global_store_dwordx4 v[92:93], v[88:91], off offset:64 nt
	s_mov_b64 s[78:79], -1
	s_nop 0
	s_waitcnt vmcnt(8)
	v_mov_b64_e32 v[88:89], v[230:231]
	v_ffbh_u32_e32 v90, v89
	v_min_u32_e32 v90, 32, v90
	v_lshlrev_b64 v[88:89], v90, v[88:89]
	v_min_u32_e32 v88, 1, v88
	v_or_b32_e32 v88, v89, v88
	v_cvt_f32_u32_e32 v88, v88
	v_sub_u32_e32 v89, 32, v90
	v_ldexp_f32 v88, v88, v89
	v_fmamk_f32 v88, v88, 0x2a800000, v204
	v_rsq_f32_e32 v88, v88
	s_nop 0
	v_pk_mul_f32 v[86:87], v[86:87], v[88:89] op_sel_hi:[1,0]
	v_pk_mul_f32 v[84:85], v[84:85], v[88:89] op_sel_hi:[1,0]
	v_pk_mul_f32 v[82:83], v[82:83], v[88:89] op_sel_hi:[1,0]
	v_pk_mul_f32 v[80:81], v[80:81], v[88:89] op_sel_hi:[1,0]
	v_pk_mul_f32 v[78:79], v[78:79], v[88:89] op_sel_hi:[1,0]
	v_pk_mul_f32 v[76:77], v[76:77], v[88:89] op_sel_hi:[1,0]
	v_pk_mul_f32 v[74:75], v[74:75], v[88:89] op_sel_hi:[1,0]
	v_pk_mul_f32 v[72:73], v[72:73], v[88:89] op_sel_hi:[1,0]
	s_cbranch_vccnz .LBB0_179
	v_mov_b64_e32 v[90:91], v[86:87]
	v_mov_b64_e32 v[98:99], v[82:83]
	v_mov_b64_e32 v[94:95], v[78:79]
	v_mov_b64_e32 v[102:103], v[74:75]
	s_and_b64 vcc, exec, s[10:11]
	v_mov_b32_e32 v106, v126
	v_mov_b64_e32 v[88:89], v[84:85]
	v_mov_b64_e32 v[96:97], v[80:81]
	v_mov_b64_e32 v[92:93], v[76:77]
	v_mov_b64_e32 v[100:101], v[72:73]
	s_cbranch_vccnz .LBB0_178
	v_cvt_f32_u32_e32 v101, v107
	s_andn2_b64 vcc, exec, s[74:75]
	v_mov_b32_e32 v106, v126
	v_mul_f32_e32 v92, v30, v101
	v_fract_f32_e32 v93, v92
	v_mul_f32_e32 v88, v28, v101
	v_mul_f32_e32 v89, v29, v101
	v_cos_f32_e32 v92, v93
	v_sin_f32_e32 v94, v93
	v_mul_f32_e32 v93, v31, v101
	v_fract_f32_e32 v90, v88
	v_fract_f32_e32 v91, v89
	v_fract_f32_e32 v95, v93
	v_cos_f32_e32 v88, v90
	v_sin_f32_e32 v90, v90
	v_cos_f32_e32 v89, v91
	v_cos_f32_e32 v93, v95
	v_sin_f32_e32 v95, v95
	v_sin_f32_e32 v91, v91
	v_pk_mul_f32 v[96:97], v[188:189], v[88:89] op_sel_hi:[0,1]
	v_pk_mul_f32 v[92:93], v[188:189], v[92:93] op_sel_hi:[0,1]
	v_pk_mul_f32 v[94:95], v[188:189], v[94:95] op_sel_hi:[0,1]
	v_pk_mul_f32 v[98:99], v[188:189], v[90:91] op_sel_hi:[0,1]
	v_pk_mul_f32 v[88:89], v[98:99], v[76:77]
	v_pk_mul_f32 v[90:91], v[94:95], v[78:79]
	v_pk_fma_f32 v[88:89], v[96:97], v[84:85], v[88:89] neg_lo:[0,0,1] neg_hi:[0,0,1]
	v_pk_fma_f32 v[90:91], v[92:93], v[86:87], v[90:91] neg_lo:[0,0,1] neg_hi:[0,0,1]
	v_pk_mul_f32 v[96:97], v[96:97], v[76:77]
	v_pk_mul_f32 v[92:93], v[92:93], v[78:79]
	v_mul_f32_e32 v100, v54, v101
	v_pk_fma_f32 v[94:95], v[94:95], v[86:87], v[92:93]
	v_pk_fma_f32 v[92:93], v[98:99], v[84:85], v[96:97]
	v_mul_f32_e32 v96, v52, v101
	v_fract_f32_e32 v97, v96
	v_cos_f32_e32 v96, v97
	v_sin_f32_e32 v98, v97
	v_mul_f32_e32 v97, v53, v101
	v_mul_f32_e32 v101, v55, v101
	v_fract_f32_e32 v99, v97
	v_fract_f32_e32 v102, v100
	v_fract_f32_e32 v103, v101
	v_cos_f32_e32 v97, v99
	v_cos_f32_e32 v100, v102
	v_sin_f32_e32 v102, v102
	v_cos_f32_e32 v101, v103
	v_sin_f32_e32 v103, v103
	v_sin_f32_e32 v99, v99
	v_pk_mul_f32 v[108:109], v[188:189], v[96:97] op_sel_hi:[0,1]
	v_pk_mul_f32 v[100:101], v[188:189], v[100:101] op_sel_hi:[0,1]
	v_pk_mul_f32 v[102:103], v[188:189], v[102:103] op_sel_hi:[0,1]
	v_pk_mul_f32 v[110:111], v[188:189], v[98:99] op_sel_hi:[0,1]
	v_pk_mul_f32 v[96:97], v[110:111], v[72:73]
	v_pk_mul_f32 v[98:99], v[102:103], v[74:75]
	v_pk_fma_f32 v[96:97], v[108:109], v[80:81], v[96:97] neg_lo:[0,0,1] neg_hi:[0,0,1]
	v_pk_fma_f32 v[98:99], v[100:101], v[82:83], v[98:99] neg_lo:[0,0,1] neg_hi:[0,0,1]
	v_pk_mul_f32 v[108:109], v[108:109], v[72:73]
	v_pk_mul_f32 v[100:101], v[100:101], v[74:75]
	s_nop 0
	v_pk_fma_f32 v[102:103], v[102:103], v[82:83], v[100:101]
	v_pk_fma_f32 v[100:101], v[110:111], v[80:81], v[108:109]
	s_cbranch_vccnz .LBB0_178
	v_pk_mul_f32 v[108:109], v[90:91], v[90:91]
	v_pk_mul_f32 v[110:111], v[88:89], v[88:89]
	v_mul_f32_e32 v106, v92, v92
	v_pk_mov_b32 v[112:113], v[110:111], v[108:109] op_sel:[1,0]
	v_mov_b32_e32 v111, v109
	v_pk_add_f32 v[108:109], v[112:113], v[110:111]
	v_pk_mul_f32 v[110:111], v[98:99], v[98:99]
	v_pk_mul_f32 v[112:113], v[96:97], v[96:97]
	v_pk_add_f32 v[108:109], v[108:109], v[108:109] op_sel_hi:[0,1]
	v_pk_mov_b32 v[114:115], v[112:113], v[110:111] op_sel:[1,0]
	v_mov_b32_e32 v113, v111
	v_pk_add_f32 v[110:111], v[114:115], v[112:113]
	v_pk_fma_f32 v[112:113], v[92:93], v[92:93], v[106:107] op_sel_hi:[1,1,0]
	v_mul_f32_e32 v106, v94, v94
	v_pk_add_f32 v[110:111], v[110:111], v[110:111] op_sel_hi:[0,1]
	v_pk_fma_f32 v[114:115], v[94:95], v[94:95], v[106:107] op_sel_hi:[1,1,0]
	v_mul_f32_e32 v112, v100, v100
	v_mul_f32_e32 v114, v101, v101
	v_mul_f32_e32 v108, v102, v102
	v_mul_f32_e32 v110, v103, v103
	v_pk_add_f32 v[112:113], v[112:113], v[114:115]
	v_pk_add_f32 v[108:109], v[108:109], v[110:111]
	s_nop 0
	v_pk_add_f32 v[108:109], v[112:113], v[108:109]
	s_nop 0
	v_add_f32_e32 v106, v108, v109
	v_and_b32_e32 v109, 64, v207
	v_xor_b32_e32 v108, 16, v207
	v_add_u32_e32 v109, 64, v109
	v_cmp_lt_i32_e32 vcc, v108, v109
	s_nop 1
	v_cndmask_b32_e32 v108, v207, v108, vcc
	v_lshlrev_b32_e32 v108, 2, v108
	ds_bpermute_b32 v108, v108, v106
	s_waitcnt lgkmcnt(0)
	v_add_f32_e32 v106, v106, v108
	v_xor_b32_e32 v108, 32, v207
	v_cmp_lt_i32_e32 vcc, v108, v109
	s_nop 1
	v_cndmask_b32_e32 v108, v207, v108, vcc
	v_lshlrev_b32_e32 v108, 2, v108
	ds_bpermute_b32 v108, v108, v106
	s_waitcnt lgkmcnt(0)
	v_add_f32_e32 v106, v106, v108
	v_max_f32_e32 v108, v126, v126
	v_max_f32_e32 v106, v108, v106

;     __device__ __forceinline__ void operator()(const f32x4 (&acc)[2][2][4][2], const Unit& u, int wr, int wc, int fr, int fq, PG8_LAS unsigned char* lds) const {
;     ...
;                 const int row = u.pm * BM + ai * HALF + wr * 64 + m * 16 + fr; const int t = row & tmask;
;                 const float rs = __builtin_amdgcn_rsqf((float)rss[row] * (2.3283064365386963e-10f / 1024.0f) + 1e-6f);
;                 f32x4 v[2][2];
; #pragma unroll
;                 for (int bj = 0; bj < 2; ++bj)
; #pragma unroll
;                     for (int n = 0; n < 2; ++n) v[bj][n] = acc[ai][bj][m][n] * rs;
;                 if (type <= 1) {
;                     float ss = 0.f;
; #pragma unroll
;                     for (int bj = 0; bj < 2; ++bj)
; #pragma unroll
;                         for (int n = 0; n < 2; ++n) { const f32x4 x = v[bj][n]; ss += (x[0] * x[0] + x[1] * x[1]) + (x[2] * x[2] + x[3] * x[3]); }
;                     ss += __shfl_xor(ss, 16); ss += __shfl_xor(ss, 32);
;                     float rn = __builtin_amdgcn_rsqf(ss * (1.0f / 64.0f) + 1e-6f); if (type == 0) rn *= QSCALE;
; #pragma unroll
;                     for (int bj = 0; bj < 2; ++bj) { const float pf = (float)(bj == 0 ? (t >> 6) : (t & 63)); f32x4 c, s;
; #pragma unroll
;                         for (int e = 0; e < 4; ++e) { const float a = __builtin_amdgcn_fractf(pf * f4[0][e]); c[e] = __builtin_amdgcn_cosf(a); s[e] = __builtin_amdgcn_sinf(a); }
;                         const f32x4 x1 = v[bj][0] * g[bj][0] * rn, x2 = v[bj][1] * g[bj][1] * rn;
;                         v[bj][0] = x1 * c - x2 * s; v[bj][1] = x1 * s + x2 * c; }
;                 } else if (type >= 3) {
;                     const float sc = type == 3 ? QSCALE : 1.0f; const float tf = (float)t;
; #pragma unroll
;                     for (int n = 0; n < 2; ++n) { f32x4 c, s;
; #pragma unroll
;                         for (int e = 0; e < 4; ++e) { const float a = __builtin_amdgcn_fractf(tf * f4[n][e]); c[e] = __builtin_amdgcn_cosf(a) * sc; s[e] = __builtin_amdgcn_sinf(a) * sc; }
;                         const f32x4 x1 = v[0][n], x2 = v[1][n];
;                         v[0][n] = x1 * c - x2 * s; v[1][n] = x1 * s + x2 * c; }
;                     if (type == 4) { float ks = 0.f;
; #pragma unroll
;                         for (int bj = 0; bj < 2; ++bj)
; #pragma unroll
.LBB0_181:
	v_lshl_add_u64 v[72:73], s[76:77], 0, v[104:105]
	v_lshlrev_b64 v[72:73], 7, v[72:73]
	v_lshl_add_u64 v[76:77], v[176:177], 0, v[72:73]
	v_cvt_pk_bf16_f32 v72, v88, v89
	v_cvt_pk_bf16_f32 v73, v90, v91
	v_cvt_pk_bf16_f32 v74, v96, v97
	v_cvt_pk_bf16_f32 v75, v98, v99
	v_add_u32_e32 v88, 0x90, v190
	v_permlane16_swap_b32_e32 v72, v74
	v_permlane16_swap_b32_e32 v73, v75
	global_store_dwordx4 v[76:77], v[72:75], off nt
	v_ashrrev_i32_e32 v89, 31, v88
	s_and_b64 vcc, exec, s[12:13]
	v_cvt_pk_bf16_f32 v72, v92, v93
	v_cvt_pk_bf16_f32 v73, v94, v95
	v_cvt_pk_bf16_f32 v74, v100, v101
	v_cvt_pk_bf16_f32 v75, v102, v103
	v_and_b32_e32 v91, s63, v88
	v_permlane16_swap_b32_e32 v72, v74
	v_permlane16_swap_b32_e32 v73, v75
	global_store_dwordx4 v[76:77], v[72:75], off offset:64 nt
	s_mov_b64 s[78:79], -1
	s_nop 0
	s_waitcnt vmcnt(10)
	v_mov_b64_e32 v[72:73], v[232:233]
	v_ffbh_u32_e32 v74, v73
	v_min_u32_e32 v74, 32, v74
	v_lshlrev_b64 v[72:73], v74, v[72:73]
	v_min_u32_e32 v72, 1, v72
	v_or_b32_e32 v72, v73, v72
	v_cvt_f32_u32_e32 v72, v72
	v_sub_u32_e32 v73, 32, v74
	v_ldexp_f32 v72, v72, v73
	v_fmamk_f32 v72, v72, 0x2a800000, v204
	v_rsq_f32_e32 v72, v72
	s_nop 0
	v_pk_mul_f32 v[70:71], v[70:71], v[72:73] op_sel_hi:[1,0]
	v_pk_mul_f32 v[68:69], v[68:69], v[72:73] op_sel_hi:[1,0]
	v_pk_mul_f32 v[66:67], v[66:67], v[72:73] op_sel_hi:[1,0]
	v_pk_mul_f32 v[64:65], v[64:65], v[72:73] op_sel_hi:[1,0]
	v_pk_mul_f32 v[62:63], v[62:63], v[72:73] op_sel_hi:[1,0]
	v_pk_mul_f32 v[60:61], v[60:61], v[72:73] op_sel_hi:[1,0]
	v_pk_mul_f32 v[58:59], v[58:59], v[72:73] op_sel_hi:[1,0]
	v_pk_mul_f32 v[56:57], v[56:57], v[72:73] op_sel_hi:[1,0]
	s_cbranch_vccnz .LBB0_186
	v_mov_b64_e32 v[74:75], v[70:71]
	v_mov_b64_e32 v[82:83], v[66:67]
	v_mov_b64_e32 v[78:79], v[62:63]
	v_mov_b64_e32 v[86:87], v[58:59]
	s_and_b64 vcc, exec, s[10:11]
	v_mov_b32_e32 v90, v106
	v_mov_b64_e32 v[72:73], v[68:69]
	v_mov_b64_e32 v[80:81], v[64:65]
	v_mov_b64_e32 v[76:77], v[60:61]
	v_mov_b64_e32 v[84:85], v[56:57]
	s_cbranch_vccnz .LBB0_185
	v_cvt_f32_u32_e32 v85, v91
	s_andn2_b64 vcc, exec, s[74:75]
	v_mov_b32_e32 v90, v106
	v_mul_f32_e32 v76, v30, v85
	v_fract_f32_e32 v77, v76
	v_mul_f32_e32 v72, v28, v85
	v_mul_f32_e32 v73, v29, v85
	v_cos_f32_e32 v76, v77
	v_sin_f32_e32 v78, v77
	v_mul_f32_e32 v77, v31, v85
	v_fract_f32_e32 v74, v72
	v_fract_f32_e32 v75, v73
	v_fract_f32_e32 v79, v77
	v_cos_f32_e32 v72, v74
	v_sin_f32_e32 v74, v74
	v_cos_f32_e32 v73, v75
	v_cos_f32_e32 v77, v79
	v_sin_f32_e32 v79, v79
	v_sin_f32_e32 v75, v75
	v_pk_mul_f32 v[80:81], v[188:189], v[72:73] op_sel_hi:[0,1]
	v_pk_mul_f32 v[76:77], v[188:189], v[76:77] op_sel_hi:[0,1]
	v_pk_mul_f32 v[78:79], v[188:189], v[78:79] op_sel_hi:[0,1]
	v_pk_mul_f32 v[82:83], v[188:189], v[74:75] op_sel_hi:[0,1]
	v_pk_mul_f32 v[72:73], v[82:83], v[60:61]
	v_pk_mul_f32 v[74:75], v[78:79], v[62:63]
	v_pk_fma_f32 v[72:73], v[80:81], v[68:69], v[72:73] neg_lo:[0,0,1] neg_hi:[0,0,1]
	v_pk_fma_f32 v[74:75], v[76:77], v[70:71], v[74:75] neg_lo:[0,0,1] neg_hi:[0,0,1]
	v_pk_mul_f32 v[80:81], v[80:81], v[60:61]
	v_pk_mul_f32 v[76:77], v[76:77], v[62:63]
	v_mul_f32_e32 v84, v54, v85
	v_pk_fma_f32 v[78:79], v[78:79], v[70:71], v[76:77]
	v_pk_fma_f32 v[76:77], v[82:83], v[68:69], v[80:81]
	v_mul_f32_e32 v80, v52, v85
	v_fract_f32_e32 v81, v80
	v_cos_f32_e32 v80, v81
	v_sin_f32_e32 v82, v81
	v_mul_f32_e32 v81, v53, v85
	v_mul_f32_e32 v85, v55, v85
	v_fract_f32_e32 v83, v81
	v_fract_f32_e32 v86, v84
	v_fract_f32_e32 v87, v85
	v_cos_f32_e32 v81, v83
	v_cos_f32_e32 v84, v86
	v_sin_f32_e32 v86, v86
	v_cos_f32_e32 v85, v87
	v_sin_f32_e32 v87, v87
	v_sin_f32_e32 v83, v83
	v_pk_mul_f32 v[92:93], v[188:189], v[80:81] op_sel_hi:[0,1]
	v_pk_mul_f32 v[84:85], v[188:189], v[84:85] op_sel_hi:[0,1]
	v_pk_mul_f32 v[86:87], v[188:189], v[86:87] op_sel_hi:[0,1]
	v_pk_mul_f32 v[94:95], v[188:189], v[82:83] op_sel_hi:[0,1]
	v_pk_mul_f32 v[80:81], v[94:95], v[56:57]
	v_pk_mul_f32 v[82:83], v[86:87], v[58:59]
	v_pk_fma_f32 v[80:81], v[92:93], v[64:65], v[80:81] neg_lo:[0,0,1] neg_hi:[0,0,1]
	v_pk_fma_f32 v[82:83], v[84:85], v[66:67], v[82:83] neg_lo:[0,0,1] neg_hi:[0,0,1]
	v_pk_mul_f32 v[92:93], v[92:93], v[56:57]
	v_pk_mul_f32 v[84:85], v[84:85], v[58:59]
	s_nop 0
	v_pk_fma_f32 v[86:87], v[86:87], v[66:67], v[84:85]
	v_pk_fma_f32 v[84:85], v[94:95], v[64:65], v[92:93]
	s_cbranch_vccnz .LBB0_185
	v_pk_mul_f32 v[92:93], v[74:75], v[74:75]
	v_pk_mul_f32 v[94:95], v[72:73], v[72:73]
	v_mul_f32_e32 v90, v76, v76
	v_pk_mov_b32 v[96:97], v[94:95], v[92:93] op_sel:[1,0]
	v_mov_b32_e32 v95, v93
	v_pk_add_f32 v[92:93], v[96:97], v[94:95]
	v_pk_mul_f32 v[94:95], v[82:83], v[82:83]
	v_pk_mul_f32 v[96:97], v[80:81], v[80:81]
	v_pk_add_f32 v[92:93], v[92:93], v[92:93] op_sel_hi:[0,1]
	v_pk_mov_b32 v[98:99], v[96:97], v[94:95] op_sel:[1,0]
	v_mov_b32_e32 v97, v95
	v_pk_add_f32 v[94:95], v[98:99], v[96:97]
	v_pk_fma_f32 v[96:97], v[76:77], v[76:77], v[90:91] op_sel_hi:[1,1,0]
	v_mul_f32_e32 v90, v78, v78
	v_pk_add_f32 v[94:95], v[94:95], v[94:95] op_sel_hi:[0,1]
	v_pk_fma_f32 v[98:99], v[78:79], v[78:79], v[90:91] op_sel_hi:[1,1,0]
	v_mul_f32_e32 v96, v84, v84
	v_mul_f32_e32 v98, v85, v85
	v_mul_f32_e32 v92, v86, v86
	v_mul_f32_e32 v94, v87, v87
	v_pk_add_f32 v[96:97], v[96:97], v[98:99]
	v_pk_add_f32 v[92:93], v[92:93], v[94:95]
	s_nop 0
	v_pk_add_f32 v[92:93], v[96:97], v[92:93]
	s_nop 0
	v_add_f32_e32 v90, v92, v93
	v_and_b32_e32 v93, 64, v207
	v_xor_b32_e32 v92, 16, v207
	v_add_u32_e32 v93, 64, v93
	v_cmp_lt_i32_e32 vcc, v92, v93
	s_nop 1
	v_cndmask_b32_e32 v92, v207, v92, vcc
	v_lshlrev_b32_e32 v92, 2, v92
	ds_bpermute_b32 v92, v92, v90
	s_waitcnt lgkmcnt(0)
	v_add_f32_e32 v90, v90, v92
	v_xor_b32_e32 v92, 32, v207
	v_cmp_lt_i32_e32 vcc, v92, v93
	s_nop 1
	v_cndmask_b32_e32 v92, v207, v92, vcc
	v_lshlrev_b32_e32 v92, 2, v92
	ds_bpermute_b32 v92, v92, v90
	s_waitcnt lgkmcnt(0)
	v_add_f32_e32 v90, v90, v92
	v_max_f32_e32 v92, v106, v106
	v_max_f32_e32 v90, v92, v90

;     __device__ __forceinline__ void operator()(const f32x4 (&acc)[2][2][4][2], const Unit& u, int wr, int wc, int fr, int fq, PG8_LAS unsigned char* lds) const {
;     ...
;                 const int row = u.pm * BM + ai * HALF + wr * 64 + m * 16 + fr; const int t = row & tmask;
;                 const float rs = __builtin_amdgcn_rsqf((float)rss[row] * (2.3283064365386963e-10f / 1024.0f) + 1e-6f);
;                 f32x4 v[2][2];
; #pragma unroll
;                 for (int bj = 0; bj < 2; ++bj)
; #pragma unroll
;                     for (int n = 0; n < 2; ++n) v[bj][n] = acc[ai][bj][m][n] * rs;
;                 if (type <= 1) {
;                     float ss = 0.f;
; #pragma unroll
;                     for (int bj = 0; bj < 2; ++bj)
; #pragma unroll
;                         for (int n = 0; n < 2; ++n) { const f32x4 x = v[bj][n]; ss += (x[0] * x[0] + x[1] * x[1]) + (x[2] * x[2] + x[3] * x[3]); }
;                     ss += __shfl_xor(ss, 16); ss += __shfl_xor(ss, 32);
;                     float rn = __builtin_amdgcn_rsqf(ss * (1.0f / 64.0f) + 1e-6f); if (type == 0) rn *= QSCALE;
; #pragma unroll
;                     for (int bj = 0; bj < 2; ++bj) { const float pf = (float)(bj == 0 ? (t >> 6) : (t & 63)); f32x4 c, s;
; #pragma unroll
;                         for (int e = 0; e < 4; ++e) { const float a = __builtin_amdgcn_fractf(pf * f4[0][e]); c[e] = __builtin_amdgcn_cosf(a); s[e] = __builtin_amdgcn_sinf(a); }
;                         const f32x4 x1 = v[bj][0] * g[bj][0] * rn, x2 = v[bj][1] * g[bj][1] * rn;
;                         v[bj][0] = x1 * c - x2 * s; v[bj][1] = x1 * s + x2 * c; }
;                 } else if (type >= 3) {
;                     const float sc = type == 3 ? QSCALE : 1.0f; const float tf = (float)t;
; #pragma unroll
;                     for (int n = 0; n < 2; ++n) { f32x4 c, s;
; #pragma unroll
;                         for (int e = 0; e < 4; ++e) { const float a = __builtin_amdgcn_fractf(tf * f4[n][e]); c[e] = __builtin_amdgcn_cosf(a) * sc; s[e] = __builtin_amdgcn_sinf(a) * sc; }
;                         const f32x4 x1 = v[0][n], x2 = v[1][n];
;                         v[0][n] = x1 * c - x2 * s; v[1][n] = x1 * s + x2 * c; }
;                     if (type == 4) { float ks = 0.f;
; #pragma unroll
;                         for (int bj = 0; bj < 2; ++bj)
; #pragma unroll
.LBB0_188:
	v_lshl_add_u64 v[56:57], s[76:77], 0, v[88:89]
	v_lshlrev_b64 v[56:57], 7, v[56:57]
	v_lshl_add_u64 v[60:61], v[176:177], 0, v[56:57]
	v_cvt_pk_bf16_f32 v56, v72, v73
	v_cvt_pk_bf16_f32 v57, v74, v75
	v_cvt_pk_bf16_f32 v58, v80, v81
	v_cvt_pk_bf16_f32 v59, v82, v83
	v_add_u32_e32 v72, 0xa0, v190
	v_permlane16_swap_b32_e32 v56, v58
	v_permlane16_swap_b32_e32 v57, v59
	global_store_dwordx4 v[60:61], v[56:59], off nt
	v_ashrrev_i32_e32 v73, 31, v72
	s_and_b64 vcc, exec, s[12:13]
	v_cvt_pk_bf16_f32 v56, v76, v77
	v_cvt_pk_bf16_f32 v57, v78, v79
	v_cvt_pk_bf16_f32 v58, v84, v85
	v_cvt_pk_bf16_f32 v59, v86, v87
	v_and_b32_e32 v75, s63, v72
	v_permlane16_swap_b32_e32 v56, v58
	v_permlane16_swap_b32_e32 v57, v59
	global_store_dwordx4 v[60:61], v[56:59], off offset:64 nt
	s_mov_b64 s[78:79], -1
	s_nop 0
	s_waitcnt vmcnt(12)
	v_mov_b64_e32 v[56:57], v[234:235]
	v_ffbh_u32_e32 v58, v57
	v_min_u32_e32 v58, 32, v58
	v_lshlrev_b64 v[56:57], v58, v[56:57]
	v_min_u32_e32 v56, 1, v56
	v_or_b32_e32 v56, v57, v56
	v_cvt_f32_u32_e32 v56, v56
	v_sub_u32_e32 v57, 32, v58
	v_ldexp_f32 v56, v56, v57
	v_fmamk_f32 v56, v56, 0x2a800000, v204
	v_rsq_f32_e32 v56, v56
	s_nop 0
	v_pk_mul_f32 v[34:35], v[34:35], v[56:57] op_sel_hi:[1,0]
	v_pk_mul_f32 v[32:33], v[32:33], v[56:57] op_sel_hi:[1,0]
	v_pk_mul_f32 v[26:27], v[26:27], v[56:57] op_sel_hi:[1,0]
	v_pk_mul_f32 v[24:25], v[24:25], v[56:57] op_sel_hi:[1,0]
	v_pk_mul_f32 v[22:23], v[22:23], v[56:57] op_sel_hi:[1,0]
	v_pk_mul_f32 v[20:21], v[20:21], v[56:57] op_sel_hi:[1,0]
	v_pk_mul_f32 v[18:19], v[18:19], v[56:57] op_sel_hi:[1,0]
	v_pk_mul_f32 v[16:17], v[16:17], v[56:57] op_sel_hi:[1,0]
	s_cbranch_vccnz .LBB0_193
	v_mov_b64_e32 v[58:59], v[34:35]
	v_mov_b64_e32 v[66:67], v[26:27]
	v_mov_b64_e32 v[62:63], v[22:23]
	v_mov_b64_e32 v[70:71], v[18:19]
	s_and_b64 vcc, exec, s[10:11]
	v_mov_b32_e32 v74, v90
	v_mov_b64_e32 v[56:57], v[32:33]
	v_mov_b64_e32 v[64:65], v[24:25]
	v_mov_b64_e32 v[60:61], v[20:21]
	v_mov_b64_e32 v[68:69], v[16:17]
	s_cbranch_vccnz .LBB0_192
	v_cvt_f32_u32_e32 v69, v75
	s_andn2_b64 vcc, exec, s[74:75]
	v_mov_b32_e32 v74, v90
	v_mul_f32_e32 v60, v30, v69
	v_fract_f32_e32 v61, v60
	v_mul_f32_e32 v56, v28, v69
	v_mul_f32_e32 v57, v29, v69
	v_cos_f32_e32 v60, v61
	v_sin_f32_e32 v62, v61
	v_mul_f32_e32 v61, v31, v69
	v_fract_f32_e32 v58, v56
	v_fract_f32_e32 v59, v57
	v_fract_f32_e32 v63, v61
	v_cos_f32_e32 v56, v58
	v_sin_f32_e32 v58, v58
	v_cos_f32_e32 v57, v59
	v_cos_f32_e32 v61, v63
	v_sin_f32_e32 v63, v63
	v_sin_f32_e32 v59, v59
	v_pk_mul_f32 v[64:65], v[188:189], v[56:57] op_sel_hi:[0,1]
	v_pk_mul_f32 v[60:61], v[188:189], v[60:61] op_sel_hi:[0,1]
	v_pk_mul_f32 v[62:63], v[188:189], v[62:63] op_sel_hi:[0,1]
	v_pk_mul_f32 v[66:67], v[188:189], v[58:59] op_sel_hi:[0,1]
	v_pk_mul_f32 v[56:57], v[66:67], v[20:21]
	v_pk_mul_f32 v[58:59], v[62:63], v[22:23]
	v_pk_fma_f32 v[56:57], v[64:65], v[32:33], v[56:57] neg_lo:[0,0,1] neg_hi:[0,0,1]
	v_pk_fma_f32 v[58:59], v[60:61], v[34:35], v[58:59] neg_lo:[0,0,1] neg_hi:[0,0,1]
	v_pk_mul_f32 v[64:65], v[64:65], v[20:21]
	v_pk_mul_f32 v[60:61], v[60:61], v[22:23]
	v_mul_f32_e32 v68, v54, v69
	v_pk_fma_f32 v[62:63], v[62:63], v[34:35], v[60:61]
	v_pk_fma_f32 v[60:61], v[66:67], v[32:33], v[64:65]
	v_mul_f32_e32 v64, v52, v69
	v_fract_f32_e32 v65, v64
	v_cos_f32_e32 v64, v65
	v_sin_f32_e32 v66, v65
	v_mul_f32_e32 v65, v53, v69
	v_mul_f32_e32 v69, v55, v69
	v_fract_f32_e32 v67, v65
	v_fract_f32_e32 v70, v68
	v_fract_f32_e32 v71, v69
	v_cos_f32_e32 v65, v67
	v_cos_f32_e32 v68, v70
	v_sin_f32_e32 v70, v70
	v_cos_f32_e32 v69, v71
	v_sin_f32_e32 v71, v71
	v_sin_f32_e32 v67, v67
	v_pk_mul_f32 v[76:77], v[188:189], v[64:65] op_sel_hi:[0,1]
	v_pk_mul_f32 v[68:69], v[188:189], v[68:69] op_sel_hi:[0,1]
	v_pk_mul_f32 v[70:71], v[188:189], v[70:71] op_sel_hi:[0,1]
	v_pk_mul_f32 v[78:79], v[188:189], v[66:67] op_sel_hi:[0,1]
	v_pk_mul_f32 v[64:65], v[78:79], v[16:17]
	v_pk_mul_f32 v[66:67], v[70:71], v[18:19]
	v_pk_fma_f32 v[64:65], v[76:77], v[24:25], v[64:65] neg_lo:[0,0,1] neg_hi:[0,0,1]
	v_pk_fma_f32 v[66:67], v[68:69], v[26:27], v[66:67] neg_lo:[0,0,1] neg_hi:[0,0,1]
	v_pk_mul_f32 v[76:77], v[76:77], v[16:17]
	v_pk_mul_f32 v[68:69], v[68:69], v[18:19]
	s_nop 0
	v_pk_fma_f32 v[70:71], v[70:71], v[26:27], v[68:69]
	v_pk_fma_f32 v[68:69], v[78:79], v[24:25], v[76:77]
	s_cbranch_vccnz .LBB0_192
	v_pk_mul_f32 v[76:77], v[58:59], v[58:59]
	v_pk_mul_f32 v[78:79], v[56:57], v[56:57]
	v_mul_f32_e32 v74, v60, v60
	v_pk_mov_b32 v[80:81], v[78:79], v[76:77] op_sel:[1,0]
	v_mov_b32_e32 v79, v77
	v_pk_add_f32 v[76:77], v[80:81], v[78:79]
	v_pk_mul_f32 v[78:79], v[66:67], v[66:67]
	v_pk_mul_f32 v[80:81], v[64:65], v[64:65]
	v_pk_add_f32 v[76:77], v[76:77], v[76:77] op_sel_hi:[0,1]
	v_pk_mov_b32 v[82:83], v[80:81], v[78:79] op_sel:[1,0]
	v_mov_b32_e32 v81, v79
	v_pk_add_f32 v[78:79], v[82:83], v[80:81]
	v_pk_fma_f32 v[80:81], v[60:61], v[60:61], v[74:75] op_sel_hi:[1,1,0]
	v_mul_f32_e32 v74, v62, v62
	v_pk_add_f32 v[78:79], v[78:79], v[78:79] op_sel_hi:[0,1]
	v_pk_fma_f32 v[82:83], v[62:63], v[62:63], v[74:75] op_sel_hi:[1,1,0]
	v_mul_f32_e32 v80, v68, v68
	v_mul_f32_e32 v82, v69, v69
	v_mul_f32_e32 v76, v70, v70
	v_mul_f32_e32 v78, v71, v71
	v_pk_add_f32 v[80:81], v[80:81], v[82:83]
	v_pk_add_f32 v[76:77], v[76:77], v[78:79]
	s_nop 0
	v_pk_add_f32 v[76:77], v[80:81], v[76:77]
	s_nop 0
	v_add_f32_e32 v74, v76, v77
	v_and_b32_e32 v77, 64, v207
	v_xor_b32_e32 v76, 16, v207
	v_add_u32_e32 v77, 64, v77
	v_cmp_lt_i32_e32 vcc, v76, v77
	s_nop 1
	v_cndmask_b32_e32 v76, v207, v76, vcc
	v_lshlrev_b32_e32 v76, 2, v76
	ds_bpermute_b32 v76, v76, v74
	s_waitcnt lgkmcnt(0)
	v_add_f32_e32 v74, v74, v76
	v_xor_b32_e32 v76, 32, v207
	v_cmp_lt_i32_e32 vcc, v76, v77
	s_nop 1
	v_cndmask_b32_e32 v76, v207, v76, vcc
	v_lshlrev_b32_e32 v76, 2, v76
	ds_bpermute_b32 v76, v76, v74
	s_waitcnt lgkmcnt(0)
	v_add_f32_e32 v74, v74, v76
	v_max_f32_e32 v76, v90, v90
	v_max_f32_e32 v74, v76, v74

;     __device__ __forceinline__ void operator()(const f32x4 (&acc)[2][2][4][2], const Unit& u, int wr, int wc, int fr, int fq, PG8_LAS unsigned char* lds) const {
;     ...
;                 const int row = u.pm * BM + ai * HALF + wr * 64 + m * 16 + fr; const int t = row & tmask;
;                 const float rs = __builtin_amdgcn_rsqf((float)rss[row] * (2.3283064365386963e-10f / 1024.0f) + 1e-6f);
;                 f32x4 v[2][2];
; #pragma unroll
;                 for (int bj = 0; bj < 2; ++bj)
; #pragma unroll
;                     for (int n = 0; n < 2; ++n) v[bj][n] = acc[ai][bj][m][n] * rs;
;                 if (type <= 1) {
;                     float ss = 0.f;
; #pragma unroll
;                     for (int bj = 0; bj < 2; ++bj)
; #pragma unroll
;                         for (int n = 0; n < 2; ++n) { const f32x4 x = v[bj][n]; ss += (x[0] * x[0] + x[1] * x[1]) + (x[2] * x[2] + x[3] * x[3]); }
;                     ss += __shfl_xor(ss, 16); ss += __shfl_xor(ss, 32);
;                     float rn = __builtin_amdgcn_rsqf(ss * (1.0f / 64.0f) + 1e-6f); if (type == 0) rn *= QSCALE;
; #pragma unroll
;                     for (int bj = 0; bj < 2; ++bj) { const float pf = (float)(bj == 0 ? (t >> 6) : (t & 63)); f32x4 c, s;
; #pragma unroll
;                         for (int e = 0; e < 4; ++e) { const float a = __builtin_amdgcn_fractf(pf * f4[0][e]); c[e] = __builtin_amdgcn_cosf(a); s[e] = __builtin_amdgcn_sinf(a); }
;                         const f32x4 x1 = v[bj][0] * g[bj][0] * rn, x2 = v[bj][1] * g[bj][1] * rn;
;                         v[bj][0] = x1 * c - x2 * s; v[bj][1] = x1 * s + x2 * c; }
;                 } else if (type >= 3) {
;                     const float sc = type == 3 ? QSCALE : 1.0f; const float tf = (float)t;
; #pragma unroll
;                     for (int n = 0; n < 2; ++n) { f32x4 c, s;
; #pragma unroll
;                         for (int e = 0; e < 4; ++e) { const float a = __builtin_amdgcn_fractf(tf * f4[n][e]); c[e] = __builtin_amdgcn_cosf(a) * sc; s[e] = __builtin_amdgcn_sinf(a) * sc; }
;                         const f32x4 x1 = v[0][n], x2 = v[1][n];
;                         v[0][n] = x1 * c - x2 * s; v[1][n] = x1 * s + x2 * c; }
;                     if (type == 4) { float ks = 0.f;
; #pragma unroll
;                         for (int bj = 0; bj < 2; ++bj)
; #pragma unroll
.LBB0_195:
	v_lshl_add_u64 v[16:17], s[76:77], 0, v[72:73]
	v_lshlrev_b64 v[16:17], 7, v[16:17]
	v_lshl_add_u64 v[20:21], v[176:177], 0, v[16:17]
	v_cvt_pk_bf16_f32 v16, v56, v57
	v_cvt_pk_bf16_f32 v17, v58, v59
	v_cvt_pk_bf16_f32 v18, v64, v65
	v_cvt_pk_bf16_f32 v19, v66, v67
	v_add_u32_e32 v56, 0xb0, v190
	v_permlane16_swap_b32_e32 v16, v18
	v_permlane16_swap_b32_e32 v17, v19
	global_store_dwordx4 v[20:21], v[16:19], off nt
	v_ashrrev_i32_e32 v57, 31, v56
	s_and_b64 vcc, exec, s[12:13]
	v_cvt_pk_bf16_f32 v16, v60, v61
	v_cvt_pk_bf16_f32 v17, v62, v63
	v_cvt_pk_bf16_f32 v18, v68, v69
	v_cvt_pk_bf16_f32 v19, v70, v71
	v_and_b32_e32 v58, s63, v56
	v_permlane16_swap_b32_e32 v16, v18
	v_permlane16_swap_b32_e32 v17, v19
	global_store_dwordx4 v[20:21], v[16:19], off offset:64 nt
	s_mov_b64 s[12:13], -1
	s_nop 0
	s_waitcnt vmcnt(14)
	v_mov_b64_e32 v[16:17], v[236:237]
	v_ffbh_u32_e32 v18, v17
	v_min_u32_e32 v18, 32, v18
	v_lshlrev_b64 v[16:17], v18, v[16:17]
	v_min_u32_e32 v16, 1, v16
	v_or_b32_e32 v16, v17, v16
	v_cvt_f32_u32_e32 v16, v16
	v_sub_u32_e32 v17, 32, v18
	v_ldexp_f32 v16, v16, v17
	v_fmamk_f32 v16, v16, 0x2a800000, v204
	v_rsq_f32_e32 v16, v16
	s_nop 0
	v_pk_mul_f32 v[14:15], v[14:15], v[16:17] op_sel_hi:[1,0]
	v_pk_mul_f32 v[12:13], v[12:13], v[16:17] op_sel_hi:[1,0]
	v_pk_mul_f32 v[10:11], v[10:11], v[16:17] op_sel_hi:[1,0]
	v_pk_mul_f32 v[8:9], v[8:9], v[16:17] op_sel_hi:[1,0]
	v_pk_mul_f32 v[6:7], v[6:7], v[16:17] op_sel_hi:[1,0]
	v_pk_mul_f32 v[4:5], v[4:5], v[16:17] op_sel_hi:[1,0]
	v_pk_mul_f32 v[2:3], v[2:3], v[16:17] op_sel_hi:[1,0]
	v_pk_mul_f32 v[0:1], v[0:1], v[16:17] op_sel_hi:[1,0]
	s_cbranch_vccnz .LBB0_200
	v_mov_b64_e32 v[18:19], v[14:15]
	v_mov_b64_e32 v[26:27], v[10:11]
	v_mov_b64_e32 v[22:23], v[6:7]
	v_mov_b64_e32 v[34:35], v[2:3]
	s_and_b64 vcc, exec, s[10:11]
	v_mov_b32_e32 v59, v74
	v_mov_b64_e32 v[16:17], v[12:13]
	v_mov_b64_e32 v[24:25], v[8:9]
	v_mov_b64_e32 v[20:21], v[4:5]
	v_mov_b64_e32 v[32:33], v[0:1]
	s_cbranch_vccnz .LBB0_199
	v_cvt_f32_u32_e32 v33, v58
	s_andn2_b64 vcc, exec, s[74:75]
	v_mov_b32_e32 v59, v74
	v_mul_f32_e32 v20, v30, v33
	v_fract_f32_e32 v21, v20
	v_mul_f32_e32 v16, v28, v33
	v_mul_f32_e32 v17, v29, v33
	v_cos_f32_e32 v20, v21
	v_sin_f32_e32 v22, v21
	v_mul_f32_e32 v21, v31, v33
	v_fract_f32_e32 v18, v16
	v_fract_f32_e32 v19, v17
	v_fract_f32_e32 v23, v21
	v_cos_f32_e32 v16, v18
	v_sin_f32_e32 v18, v18
	v_cos_f32_e32 v17, v19
	v_cos_f32_e32 v21, v23
	v_sin_f32_e32 v23, v23
	v_sin_f32_e32 v19, v19
	v_pk_mul_f32 v[24:25], v[188:189], v[16:17] op_sel_hi:[0,1]
	v_pk_mul_f32 v[20:21], v[188:189], v[20:21] op_sel_hi:[0,1]
	v_pk_mul_f32 v[22:23], v[188:189], v[22:23] op_sel_hi:[0,1]
	v_pk_mul_f32 v[26:27], v[188:189], v[18:19] op_sel_hi:[0,1]
	v_pk_mul_f32 v[16:17], v[26:27], v[4:5]
	v_pk_mul_f32 v[18:19], v[22:23], v[6:7]
	v_pk_fma_f32 v[16:17], v[24:25], v[12:13], v[16:17] neg_lo:[0,0,1] neg_hi:[0,0,1]
	v_pk_fma_f32 v[18:19], v[20:21], v[14:15], v[18:19] neg_lo:[0,0,1] neg_hi:[0,0,1]
	v_pk_mul_f32 v[24:25], v[24:25], v[4:5]
	v_pk_mul_f32 v[20:21], v[20:21], v[6:7]
	v_mul_f32_e32 v32, v54, v33
	v_pk_fma_f32 v[22:23], v[22:23], v[14:15], v[20:21]
	v_pk_fma_f32 v[20:21], v[26:27], v[12:13], v[24:25]
	v_mul_f32_e32 v24, v52, v33
	v_fract_f32_e32 v25, v24
	v_cos_f32_e32 v24, v25
	v_sin_f32_e32 v26, v25
	v_mul_f32_e32 v25, v53, v33
	v_mul_f32_e32 v33, v55, v33
	v_fract_f32_e32 v27, v25
	v_fract_f32_e32 v34, v32
	v_fract_f32_e32 v35, v33
	v_cos_f32_e32 v25, v27
	v_cos_f32_e32 v32, v34
	v_sin_f32_e32 v34, v34
	v_cos_f32_e32 v33, v35
	v_sin_f32_e32 v35, v35
	v_sin_f32_e32 v27, v27
	v_pk_mul_f32 v[52:53], v[188:189], v[24:25] op_sel_hi:[0,1]
	v_pk_mul_f32 v[32:33], v[188:189], v[32:33] op_sel_hi:[0,1]
	v_pk_mul_f32 v[34:35], v[188:189], v[34:35] op_sel_hi:[0,1]
	v_pk_mul_f32 v[54:55], v[188:189], v[26:27] op_sel_hi:[0,1]
	v_pk_mul_f32 v[24:25], v[54:55], v[0:1]
	v_pk_mul_f32 v[26:27], v[34:35], v[2:3]
	v_pk_fma_f32 v[24:25], v[52:53], v[8:9], v[24:25] neg_lo:[0,0,1] neg_hi:[0,0,1]
	v_pk_fma_f32 v[26:27], v[32:33], v[10:11], v[26:27] neg_lo:[0,0,1] neg_hi:[0,0,1]
	v_pk_mul_f32 v[52:53], v[52:53], v[0:1]
	v_pk_mul_f32 v[32:33], v[32:33], v[2:3]
	s_nop 0
	v_pk_fma_f32 v[34:35], v[34:35], v[10:11], v[32:33]
	v_pk_fma_f32 v[32:33], v[54:55], v[8:9], v[52:53]
	s_cbranch_vccnz .LBB0_199
	v_pk_mul_f32 v[52:53], v[18:19], v[18:19]
	v_pk_mul_f32 v[54:55], v[16:17], v[16:17]
	s_nop 0
	v_pk_mov_b32 v[60:61], v[54:55], v[52:53] op_sel:[1,0]
	v_mov_b32_e32 v55, v53
	v_pk_add_f32 v[52:53], v[60:61], v[54:55]
	v_pk_mul_f32 v[54:55], v[26:27], v[26:27]
	v_pk_add_f32 v[52:53], v[52:53], v[52:53] op_sel_hi:[0,1]
	v_pk_mul_f32 v[60:61], v[24:25], v[24:25]
	v_mul_f32_e32 v52, v20, v20
	v_pk_mov_b32 v[62:63], v[60:61], v[54:55] op_sel:[1,0]
	v_mov_b32_e32 v61, v55
	v_pk_add_f32 v[54:55], v[62:63], v[60:61]
	v_pk_fma_f32 v[60:61], v[20:21], v[20:21], v[52:53] op_sel_hi:[1,1,0]
	v_mul_f32_e32 v52, v22, v22
	v_pk_add_f32 v[54:55], v[54:55], v[54:55] op_sel_hi:[0,1]
	v_pk_fma_f32 v[62:63], v[22:23], v[22:23], v[52:53] op_sel_hi:[1,1,0]
	v_mul_f32_e32 v60, v32, v32
	v_mul_f32_e32 v62, v33, v33
	v_mul_f32_e32 v52, v34, v34
	v_mul_f32_e32 v54, v35, v35
	v_pk_add_f32 v[60:61], v[60:61], v[62:63]
	v_pk_add_f32 v[52:53], v[52:53], v[54:55]
	v_and_b32_e32 v54, 64, v207
	v_pk_add_f32 v[52:53], v[60:61], v[52:53]
	v_add_u32_e32 v54, 64, v54
	v_add_f32_e32 v52, v52, v53
	v_xor_b32_e32 v53, 16, v207
	v_cmp_lt_i32_e32 vcc, v53, v54
	s_nop 1
	v_cndmask_b32_e32 v53, v207, v53, vcc
	v_lshlrev_b32_e32 v53, 2, v53
	ds_bpermute_b32 v53, v53, v52
	s_waitcnt lgkmcnt(0)
	v_add_f32_e32 v52, v52, v53
	v_xor_b32_e32 v53, 32, v207
	v_cmp_lt_i32_e32 vcc, v53, v54
	s_nop 1
	v_cndmask_b32_e32 v53, v207, v53, vcc
	v_lshlrev_b32_e32 v53, 2, v53
	ds_bpermute_b32 v53, v53, v52
	s_waitcnt lgkmcnt(0)
	v_add_f32_e32 v52, v52, v53
	v_max_f32_e32 v53, v74, v74
	v_max_f32_e32 v59, v53, v52

; __device__ __forceinline__ unsigned cvt_pk_bf16(float lo, float hi) { unsigned r; asm volatile("v_cvt_pk_bf16_f32 %0, %1, %2" : "=v"(r) : "v"(lo), "v"(hi)); return r; }
;     __device__ __forceinline__ void operator()(const f32x4 (&acc)[2][2][4][2], const Unit& u, int wr, int wc, int fr, int fq, PG8_LAS unsigned char* lds) const {
;     ...
;                 bf16_t* rowp = P + ((size_t)slot * 81920 + row) * 64 + (((fq & 1) << 4) + ((fq >> 1) << 3));
; #pragma unroll
;                 for (int bj = 0; bj < 2; ++bj) {
;                     unsigned a0 = cvt_pk_bf16(v[bj][0][0], v[bj][0][1]), a1 = cvt_pk_bf16(v[bj][0][2], v[bj][0][3]), b0 = cvt_pk_bf16(v[bj][1][0], v[bj][1][1]), b1 = cvt_pk_bf16(v[bj][1][2], v[bj][1][3]);
;                     { auto r = __builtin_amdgcn_permlane16_swap(a0, b0, false, false); a0 = r[0]; b0 = r[1]; }
;                     { auto r = __builtin_amdgcn_permlane16_swap(a1, b1, false, false); a1 = r[0]; b1 = r[1]; }
;                     u32x4 w; w.x = a0; w.y = a1; w.z = b0; w.w = b1; *(u32x4*)(rowp + 32 * bj) = w; }
;             }
;         if (type == 4) {
; #pragma unroll
;             for (int o = 1; o < 16; o <<= 1) kmx = __builtin_fmaxf(kmx, __shfl_xor(kmx, o));
;             const int r0 = u.pm * BM; const int seq = r0 < TPROMPT ? (r0 >> 11) : 32 + ((r0 - TPROMPT) >> 12);
;             if (fr == 0 && fq == 0) atomicMax(kmax + seq * 8 + (slot - 20), __float_as_uint(kmx));
.LBB0_202:
	v_lshl_add_u64 v[0:1], s[76:77], 0, v[56:57]
	v_lshlrev_b64 v[0:1], 7, v[0:1]
	v_lshl_add_u64 v[4:5], v[176:177], 0, v[0:1]
	v_cvt_pk_bf16_f32 v0, v16, v17
	v_cvt_pk_bf16_f32 v1, v18, v19
	v_cvt_pk_bf16_f32 v2, v24, v25
	v_cvt_pk_bf16_f32 v3, v26, v27
	s_and_b64 vcc, exec, s[74:75]
	v_permlane16_swap_b32_e32 v0, v2
	v_permlane16_swap_b32_e32 v1, v3
	global_store_dwordx4 v[4:5], v[0:3], off nt
	s_nop 1
	v_cvt_pk_bf16_f32 v0, v20, v21
	v_cvt_pk_bf16_f32 v1, v22, v23
	v_cvt_pk_bf16_f32 v2, v32, v33
	v_cvt_pk_bf16_f32 v3, v34, v35
	s_nop 0
	v_permlane16_swap_b32_e32 v0, v2
	v_permlane16_swap_b32_e32 v1, v3
	global_store_dwordx4 v[4:5], v[0:3], off offset:64 nt
	s_cbranch_vccz .LBB0_209
	s_nop 0
	v_and_b32_e32 v0, 64, v207
	v_add_u32_e32 v1, 64, v0
	v_xor_b32_e32 v0, 1, v207
	v_cmp_lt_i32_e32 vcc, v0, v1
	v_xor_b32_e32 v3, 2, v207
	v_max_f32_e32 v2, v59, v59
	v_cndmask_b32_e32 v0, v207, v0, vcc
	v_lshlrev_b32_e32 v0, 2, v0
	ds_bpermute_b32 v0, v0, v59
	v_cmp_lt_i32_e32 vcc, v3, v1
	s_waitcnt lgkmcnt(0)
	v_max_f32_e32 v0, v0, v0
	v_max_f32_e32 v0, v2, v0
	v_cndmask_b32_e32 v2, v207, v3, vcc
	v_lshlrev_b32_e32 v2, 2, v2
	ds_bpermute_b32 v2, v2, v0
	v_xor_b32_e32 v3, 4, v207
	v_cmp_lt_i32_e32 vcc, v3, v1
	s_waitcnt lgkmcnt(0)
	v_max_f32_e32 v2, v2, v2
	v_max_f32_e32 v0, v0, v2
	v_cndmask_b32_e32 v2, v207, v3, vcc
	v_lshlrev_b32_e32 v2, 2, v2
	ds_bpermute_b32 v2, v2, v0
	v_xor_b32_e32 v3, 8, v207
	v_cmp_lt_i32_e32 vcc, v3, v1
	s_waitcnt lgkmcnt(0)
	v_max_f32_e32 v2, v2, v2
	v_cndmask_b32_e32 v1, v207, v3, vcc
	v_max_f32_e32 v0, v0, v2
	v_lshlrev_b32_e32 v1, 2, v1
	ds_bpermute_b32 v1, v1, v0
	s_and_saveexec_b64 s[8:9], s[4:5]
	s_cbranch_execz .LBB0_208
	s_waitcnt lgkmcnt(0)
	v_max_f32_e32 v1, v1, v1
	v_max_f32_e32 v0, v0, v0
	s_mov_b64 s[10:11], exec
	s_ashr_i32 s71, s70, 31
	v_max_f32_e32 v0, v0, v1
	s_mov_b32 s12, 0

;     __device__ __forceinline__ void operator()(const f32x4 (&acc)[2][2][4][2], const Unit& u, int wr, int wc, int fr, int fq, PG8_LAS unsigned char* lds) const {
;     ...
;                 const int row = u.pm * BM + ai * HALF + wr * 64 + m * 16 + fr; const int t = row & tmask;
;                 const float rs = __builtin_amdgcn_rsqf((float)rss[row] * (2.3283064365386963e-10f / 1024.0f) + 1e-6f);
;                 f32x4 v[2][2];
; #pragma unroll
;                 for (int bj = 0; bj < 2; ++bj)
; #pragma unroll
;                     for (int n = 0; n < 2; ++n) v[bj][n] = acc[ai][bj][m][n] * rs;
;                 if (type <= 1) {
;                     float ss = 0.f;
; #pragma unroll
;                     for (int bj = 0; bj < 2; ++bj)
; #pragma unroll
;                         for (int n = 0; n < 2; ++n) { const f32x4 x = v[bj][n]; ss += (x[0] * x[0] + x[1] * x[1]) + (x[2] * x[2] + x[3] * x[3]); }
;                     ss += __shfl_xor(ss, 16); ss += __shfl_xor(ss, 32);
;                     float rn = __builtin_amdgcn_rsqf(ss * (1.0f / 64.0f) + 1e-6f); if (type == 0) rn *= QSCALE;
; #pragma unroll
;                     for (int bj = 0; bj < 2; ++bj) { const float pf = (float)(bj == 0 ? (t >> 6) : (t & 63)); f32x4 c, s;
; #pragma unroll
;                         for (int e = 0; e < 4; ++e) { const float a = __builtin_amdgcn_fractf(pf * f4[0][e]); c[e] = __builtin_amdgcn_cosf(a); s[e] = __builtin_amdgcn_sinf(a); }
;                         const f32x4 x1 = v[bj][0] * g[bj][0] * rn, x2 = v[bj][1] * g[bj][1] * rn;
;                         v[bj][0] = x1 * c - x2 * s; v[bj][1] = x1 * s + x2 * c; }
;                 } else if (type >= 3) {
;                     const float sc = type == 3 ? QSCALE : 1.0f; const float tf = (float)t;
; #pragma unroll
;                     for (int n = 0; n < 2; ++n) { f32x4 c, s;
; #pragma unroll
;                         for (int e = 0; e < 4; ++e) { const float a = __builtin_amdgcn_fractf(tf * f4[n][e]); c[e] = __builtin_amdgcn_cosf(a) * sc; s[e] = __builtin_amdgcn_sinf(a) * sc; }
;                         const f32x4 x1 = v[0][n], x2 = v[1][n];
;                         v[0][n] = x1 * c - x2 * s; v[1][n] = x1 * s + x2 * c; }
;                     if (type == 4) { float ks = 0.f;
; #pragma unroll
;                         for (int bj = 0; bj < 2; ++bj)
; #pragma unroll
.LBB0_706:
	v_mad_i64_i32 v[136:137], s[12:13], s74, v208, v[190:191]
	v_lshlrev_b64 v[136:137], 7, v[136:137]
	v_lshl_add_u64 v[140:141], v[176:177], 0, v[136:137]
	v_cvt_pk_bf16_f32 v136, v152, v153
	v_cvt_pk_bf16_f32 v137, v154, v155
	v_cvt_pk_bf16_f32 v138, v160, v161
	v_cvt_pk_bf16_f32 v139, v162, v163
	v_add_u32_e32 v152, s67, v194
	v_permlane16_swap_b32_e32 v136, v138
	v_permlane16_swap_b32_e32 v137, v139
	global_store_dwordx4 v[140:141], v[136:139], off nt
	v_ashrrev_i32_e32 v153, 31, v152
	s_andn2_b64 vcc, exec, s[80:81]
	v_cvt_pk_bf16_f32 v136, v156, v157
	v_cvt_pk_bf16_f32 v137, v158, v159
	v_cvt_pk_bf16_f32 v138, v164, v165
	v_cvt_pk_bf16_f32 v139, v166, v167
	v_and_b32_e32 v159, s69, v152
	v_permlane16_swap_b32_e32 v136, v138
	v_permlane16_swap_b32_e32 v137, v139
	global_store_dwordx4 v[140:141], v[136:139], off offset:64 nt
	s_nop 1
	s_waitcnt vmcnt(2)
	v_mov_b64_e32 v[136:137], v[224:225]
	v_ffbh_u32_e32 v138, v137
	v_min_u32_e32 v138, 32, v138
	v_lshlrev_b64 v[136:137], v138, v[136:137]
	v_min_u32_e32 v136, 1, v136
	v_or_b32_e32 v136, v137, v136
	v_cvt_f32_u32_e32 v136, v136
	v_sub_u32_e32 v138, 32, v138
	v_cndmask_b32_e64 v137, 0, 1, s[80:81]
	v_cmp_ne_u32_e64 s[12:13], 1, v137
	v_ldexp_f32 v136, v136, v138
	v_fmamk_f32 v136, v136, 0x2a800000, v204
	v_rsq_f32_e32 v136, v136
	s_mov_b64 s[80:81], -1
	v_pk_mul_f32 v[134:135], v[134:135], v[136:137] op_sel_hi:[1,0]
	v_pk_mul_f32 v[132:133], v[132:133], v[136:137] op_sel_hi:[1,0]
	v_pk_mul_f32 v[130:131], v[130:131], v[136:137] op_sel_hi:[1,0]
	v_pk_mul_f32 v[128:129], v[128:129], v[136:137] op_sel_hi:[1,0]
	v_pk_mul_f32 v[126:127], v[126:127], v[136:137] op_sel_hi:[1,0]
	v_pk_mul_f32 v[124:125], v[124:125], v[136:137] op_sel_hi:[1,0]
	v_pk_mul_f32 v[122:123], v[122:123], v[136:137] op_sel_hi:[1,0]
	v_pk_mul_f32 v[120:121], v[120:121], v[136:137] op_sel_hi:[1,0]
	s_cbranch_vccnz .LBB0_711
	v_mov_b64_e32 v[138:139], v[134:135]
	v_mov_b64_e32 v[146:147], v[130:131]
	v_mov_b64_e32 v[142:143], v[126:127]
	v_mov_b64_e32 v[150:151], v[122:123]
	s_and_b64 vcc, exec, s[10:11]
	v_mov_b32_e32 v158, v213
	v_mov_b64_e32 v[136:137], v[132:133]
	v_mov_b64_e32 v[144:145], v[128:129]
	v_mov_b64_e32 v[140:141], v[124:125]
	v_mov_b64_e32 v[148:149], v[120:121]
	s_cbranch_vccnz .LBB0_710
	v_cvt_f32_u32_e32 v149, v159
	s_andn2_b64 vcc, exec, s[78:79]
	v_mov_b32_e32 v158, v213
	v_mul_f32_e32 v140, v30, v149
	v_fract_f32_e32 v141, v140
	v_mul_f32_e32 v136, v28, v149
	v_mul_f32_e32 v137, v29, v149
	v_cos_f32_e32 v140, v141
	v_sin_f32_e32 v142, v141
	v_mul_f32_e32 v141, v31, v149
	v_fract_f32_e32 v138, v136
	v_fract_f32_e32 v139, v137
	v_fract_f32_e32 v143, v141
	v_cos_f32_e32 v136, v138
	v_sin_f32_e32 v138, v138
	v_cos_f32_e32 v137, v139
	v_cos_f32_e32 v141, v143
	v_sin_f32_e32 v143, v143
	v_sin_f32_e32 v139, v139
	v_pk_mul_f32 v[144:145], v[188:189], v[136:137] op_sel_hi:[0,1]
	v_pk_mul_f32 v[140:141], v[188:189], v[140:141] op_sel_hi:[0,1]
	v_pk_mul_f32 v[142:143], v[188:189], v[142:143] op_sel_hi:[0,1]
	v_pk_mul_f32 v[146:147], v[188:189], v[138:139] op_sel_hi:[0,1]
	v_pk_mul_f32 v[136:137], v[146:147], v[124:125]
	v_pk_mul_f32 v[138:139], v[142:143], v[126:127]
	v_pk_fma_f32 v[136:137], v[144:145], v[132:133], v[136:137] neg_lo:[0,0,1] neg_hi:[0,0,1]
	v_pk_fma_f32 v[138:139], v[140:141], v[134:135], v[138:139] neg_lo:[0,0,1] neg_hi:[0,0,1]
	v_pk_mul_f32 v[144:145], v[144:145], v[124:125]
	v_pk_mul_f32 v[140:141], v[140:141], v[126:127]
	v_mul_f32_e32 v148, v54, v149
	v_pk_fma_f32 v[142:143], v[142:143], v[134:135], v[140:141]
	v_pk_fma_f32 v[140:141], v[146:147], v[132:133], v[144:145]
	v_mul_f32_e32 v144, v52, v149
	v_fract_f32_e32 v145, v144
	v_cos_f32_e32 v144, v145
	v_sin_f32_e32 v146, v145
	v_mul_f32_e32 v145, v53, v149
	v_mul_f32_e32 v149, v55, v149
	v_fract_f32_e32 v147, v145
	v_fract_f32_e32 v150, v148
	v_fract_f32_e32 v151, v149
	v_cos_f32_e32 v145, v147
	v_cos_f32_e32 v148, v150
	v_sin_f32_e32 v150, v150
	v_cos_f32_e32 v149, v151
	v_sin_f32_e32 v151, v151
	v_sin_f32_e32 v147, v147
	v_pk_mul_f32 v[154:155], v[188:189], v[144:145] op_sel_hi:[0,1]
	v_pk_mul_f32 v[148:149], v[188:189], v[148:149] op_sel_hi:[0,1]
	v_pk_mul_f32 v[150:151], v[188:189], v[150:151] op_sel_hi:[0,1]
	v_pk_mul_f32 v[156:157], v[188:189], v[146:147] op_sel_hi:[0,1]
	v_pk_mul_f32 v[144:145], v[156:157], v[120:121]
	v_pk_mul_f32 v[146:147], v[150:151], v[122:123]
	v_pk_fma_f32 v[144:145], v[154:155], v[128:129], v[144:145] neg_lo:[0,0,1] neg_hi:[0,0,1]
	v_pk_fma_f32 v[146:147], v[148:149], v[130:131], v[146:147] neg_lo:[0,0,1] neg_hi:[0,0,1]
	v_pk_mul_f32 v[154:155], v[154:155], v[120:121]
	v_pk_mul_f32 v[148:149], v[148:149], v[122:123]
	s_nop 0
	v_pk_fma_f32 v[150:151], v[150:151], v[130:131], v[148:149]
	v_pk_fma_f32 v[148:149], v[156:157], v[128:129], v[154:155]
	s_cbranch_vccnz .LBB0_710
	v_pk_mul_f32 v[154:155], v[138:139], v[138:139]
	v_pk_mul_f32 v[156:157], v[136:137], v[136:137]
	s_nop 0
	v_pk_mov_b32 v[160:161], v[156:157], v[154:155] op_sel:[1,0]
	v_mov_b32_e32 v157, v155
	v_pk_add_f32 v[154:155], v[160:161], v[156:157]
	v_pk_mul_f32 v[156:157], v[146:147], v[146:147]
	v_pk_add_f32 v[154:155], v[154:155], v[154:155] op_sel_hi:[0,1]
	v_pk_mul_f32 v[160:161], v[144:145], v[144:145]
	v_mul_f32_e32 v154, v140, v140
	v_pk_mov_b32 v[162:163], v[160:161], v[156:157] op_sel:[1,0]
	v_mov_b32_e32 v161, v157
	v_pk_add_f32 v[156:157], v[162:163], v[160:161]
	v_pk_fma_f32 v[160:161], v[140:141], v[140:141], v[154:155] op_sel_hi:[1,1,0]
	v_mul_f32_e32 v154, v142, v142
	v_pk_add_f32 v[156:157], v[156:157], v[156:157] op_sel_hi:[0,1]
	v_pk_fma_f32 v[162:163], v[142:143], v[142:143], v[154:155] op_sel_hi:[1,1,0]
	v_mul_f32_e32 v160, v148, v148
	v_mul_f32_e32 v162, v149, v149
	v_mul_f32_e32 v154, v150, v150
	v_mul_f32_e32 v156, v151, v151
	v_pk_add_f32 v[160:161], v[160:161], v[162:163]
	v_pk_add_f32 v[154:155], v[154:155], v[156:157]
	v_and_b32_e32 v156, 64, v207
	v_pk_add_f32 v[154:155], v[160:161], v[154:155]
	v_add_u32_e32 v156, 64, v156
	v_add_f32_e32 v154, v154, v155
	v_xor_b32_e32 v155, 16, v207
	v_cmp_lt_i32_e32 vcc, v155, v156
	s_nop 1
	v_cndmask_b32_e32 v155, v207, v155, vcc
	v_lshlrev_b32_e32 v155, 2, v155
	ds_bpermute_b32 v155, v155, v154
	s_waitcnt lgkmcnt(0)
	v_add_f32_e32 v154, v154, v155
	v_xor_b32_e32 v155, 32, v207
	v_cmp_lt_i32_e32 vcc, v155, v156
	s_nop 1
	v_cndmask_b32_e32 v155, v207, v155, vcc
	v_lshlrev_b32_e32 v155, 2, v155
	ds_bpermute_b32 v155, v155, v154
	s_waitcnt lgkmcnt(0)
	v_add_f32_e32 v154, v154, v155
	v_max_f32_e32 v155, v213, v213
	v_max_f32_e32 v158, v155, v154

;     __device__ __forceinline__ void operator()(const f32x4 (&acc)[2][2][4][2], const Unit& u, int wr, int wc, int fr, int fq, PG8_LAS unsigned char* lds) const {
;     ...
;                 const int row = u.pm * BM + ai * HALF + wr * 64 + m * 16 + fr; const int t = row & tmask;
;                 const float rs = __builtin_amdgcn_rsqf((float)rss[row] * (2.3283064365386963e-10f / 1024.0f) + 1e-6f);
;                 f32x4 v[2][2];
; #pragma unroll
;                 for (int bj = 0; bj < 2; ++bj)
; #pragma unroll
;                     for (int n = 0; n < 2; ++n) v[bj][n] = acc[ai][bj][m][n] * rs;
;                 if (type <= 1) {
;                     float ss = 0.f;
; #pragma unroll
;                     for (int bj = 0; bj < 2; ++bj)
; #pragma unroll
;                         for (int n = 0; n < 2; ++n) { const f32x4 x = v[bj][n]; ss += (x[0] * x[0] + x[1] * x[1]) + (x[2] * x[2] + x[3] * x[3]); }
;                     ss += __shfl_xor(ss, 16); ss += __shfl_xor(ss, 32);
;                     float rn = __builtin_amdgcn_rsqf(ss * (1.0f / 64.0f) + 1e-6f); if (type == 0) rn *= QSCALE;
; #pragma unroll
;                     for (int bj = 0; bj < 2; ++bj) { const float pf = (float)(bj == 0 ? (t >> 6) : (t & 63)); f32x4 c, s;
; #pragma unroll
;                         for (int e = 0; e < 4; ++e) { const float a = __builtin_amdgcn_fractf(pf * f4[0][e]); c[e] = __builtin_amdgcn_cosf(a); s[e] = __builtin_amdgcn_sinf(a); }
;                         const f32x4 x1 = v[bj][0] * g[bj][0] * rn, x2 = v[bj][1] * g[bj][1] * rn;
;                         v[bj][0] = x1 * c - x2 * s; v[bj][1] = x1 * s + x2 * c; }
;                 } else if (type >= 3) {
;                     const float sc = type == 3 ? QSCALE : 1.0f; const float tf = (float)t;
; #pragma unroll
;                     for (int n = 0; n < 2; ++n) { f32x4 c, s;
; #pragma unroll
;                         for (int e = 0; e < 4; ++e) { const float a = __builtin_amdgcn_fractf(tf * f4[n][e]); c[e] = __builtin_amdgcn_cosf(a) * sc; s[e] = __builtin_amdgcn_sinf(a) * sc; }
;                         const f32x4 x1 = v[0][n], x2 = v[1][n];
;                         v[0][n] = x1 * c - x2 * s; v[1][n] = x1 * s + x2 * c; }
;                     if (type == 4) { float ks = 0.f;
; #pragma unroll
;                         for (int bj = 0; bj < 2; ++bj)
; #pragma unroll
.LBB0_713:
	s_mul_hi_i32 s81, s74, 0x14000
	s_mul_i32 s80, s74, 0x14000
	v_lshl_add_u64 v[120:121], s[80:81], 0, v[152:153]
	v_lshlrev_b64 v[120:121], 7, v[120:121]
	v_lshl_add_u64 v[124:125], v[176:177], 0, v[120:121]
	v_cvt_pk_bf16_f32 v120, v136, v137
	v_cvt_pk_bf16_f32 v121, v138, v139
	v_cvt_pk_bf16_f32 v122, v144, v145
	v_cvt_pk_bf16_f32 v123, v146, v147
	v_add_u32_e32 v136, s67, v196
	v_permlane16_swap_b32_e32 v120, v122
	v_permlane16_swap_b32_e32 v121, v123
	global_store_dwordx4 v[124:125], v[120:123], off nt
	v_ashrrev_i32_e32 v137, 31, v136
	s_and_b64 vcc, exec, s[12:13]
	v_cvt_pk_bf16_f32 v120, v140, v141
	v_cvt_pk_bf16_f32 v121, v142, v143
	v_cvt_pk_bf16_f32 v122, v148, v149
	v_cvt_pk_bf16_f32 v123, v150, v151
	v_and_b32_e32 v143, s69, v136
	v_permlane16_swap_b32_e32 v120, v122
	v_permlane16_swap_b32_e32 v121, v123
	global_store_dwordx4 v[124:125], v[120:123], off offset:64 nt
	s_mov_b64 s[82:83], -1
	s_nop 0
	s_waitcnt vmcnt(4)
	v_mov_b64_e32 v[120:121], v[226:227]
	v_ffbh_u32_e32 v122, v121
	v_min_u32_e32 v122, 32, v122
	v_lshlrev_b64 v[120:121], v122, v[120:121]
	v_min_u32_e32 v120, 1, v120
	v_or_b32_e32 v120, v121, v120
	v_cvt_f32_u32_e32 v120, v120
	v_sub_u32_e32 v121, 32, v122
	v_ldexp_f32 v120, v120, v121
	v_fmamk_f32 v120, v120, 0x2a800000, v204
	v_rsq_f32_e32 v120, v120
	s_nop 0
	v_pk_mul_f32 v[118:119], v[118:119], v[120:121] op_sel_hi:[1,0]
	v_pk_mul_f32 v[116:117], v[116:117], v[120:121] op_sel_hi:[1,0]
	v_pk_mul_f32 v[114:115], v[114:115], v[120:121] op_sel_hi:[1,0]
	v_pk_mul_f32 v[112:113], v[112:113], v[120:121] op_sel_hi:[1,0]
	v_pk_mul_f32 v[110:111], v[110:111], v[120:121] op_sel_hi:[1,0]
	v_pk_mul_f32 v[108:109], v[108:109], v[120:121] op_sel_hi:[1,0]
	v_pk_mul_f32 v[106:107], v[106:107], v[120:121] op_sel_hi:[1,0]
	v_pk_mul_f32 v[104:105], v[104:105], v[120:121] op_sel_hi:[1,0]
	s_cbranch_vccnz .LBB0_718
	v_mov_b64_e32 v[122:123], v[118:119]
	v_mov_b64_e32 v[130:131], v[114:115]
	v_mov_b64_e32 v[126:127], v[110:111]
	v_mov_b64_e32 v[134:135], v[106:107]
	s_and_b64 vcc, exec, s[10:11]
	v_mov_b32_e32 v142, v158
	v_mov_b64_e32 v[120:121], v[116:117]
	v_mov_b64_e32 v[128:129], v[112:113]
	v_mov_b64_e32 v[124:125], v[108:109]
	v_mov_b64_e32 v[132:133], v[104:105]
	s_cbranch_vccnz .LBB0_717
	v_cvt_f32_u32_e32 v133, v143
	s_andn2_b64 vcc, exec, s[78:79]
	v_mov_b32_e32 v142, v158
	v_mul_f32_e32 v124, v30, v133
	v_fract_f32_e32 v125, v124
	v_mul_f32_e32 v120, v28, v133
	v_mul_f32_e32 v121, v29, v133
	v_cos_f32_e32 v124, v125
	v_sin_f32_e32 v126, v125
	v_mul_f32_e32 v125, v31, v133
	v_fract_f32_e32 v122, v120
	v_fract_f32_e32 v123, v121
	v_fract_f32_e32 v127, v125
	v_cos_f32_e32 v120, v122
	v_sin_f32_e32 v122, v122
	v_cos_f32_e32 v121, v123
	v_cos_f32_e32 v125, v127
	v_sin_f32_e32 v127, v127
	v_sin_f32_e32 v123, v123
	v_pk_mul_f32 v[128:129], v[188:189], v[120:121] op_sel_hi:[0,1]
	v_pk_mul_f32 v[124:125], v[188:189], v[124:125] op_sel_hi:[0,1]
	v_pk_mul_f32 v[126:127], v[188:189], v[126:127] op_sel_hi:[0,1]
	v_pk_mul_f32 v[130:131], v[188:189], v[122:123] op_sel_hi:[0,1]
	v_pk_mul_f32 v[120:121], v[130:131], v[108:109]
	v_pk_mul_f32 v[122:123], v[126:127], v[110:111]
	v_pk_fma_f32 v[120:121], v[128:129], v[116:117], v[120:121] neg_lo:[0,0,1] neg_hi:[0,0,1]
	v_pk_fma_f32 v[122:123], v[124:125], v[118:119], v[122:123] neg_lo:[0,0,1] neg_hi:[0,0,1]
	v_pk_mul_f32 v[128:129], v[128:129], v[108:109]
	v_pk_mul_f32 v[124:125], v[124:125], v[110:111]
	v_mul_f32_e32 v132, v54, v133
	v_pk_fma_f32 v[126:127], v[126:127], v[118:119], v[124:125]
	v_pk_fma_f32 v[124:125], v[130:131], v[116:117], v[128:129]
	v_mul_f32_e32 v128, v52, v133
	v_fract_f32_e32 v129, v128
	v_cos_f32_e32 v128, v129
	v_sin_f32_e32 v130, v129
	v_mul_f32_e32 v129, v53, v133
	v_mul_f32_e32 v133, v55, v133
	v_fract_f32_e32 v131, v129
	v_fract_f32_e32 v134, v132
	v_fract_f32_e32 v135, v133
	v_cos_f32_e32 v129, v131
	v_cos_f32_e32 v132, v134
	v_sin_f32_e32 v134, v134
	v_cos_f32_e32 v133, v135
	v_sin_f32_e32 v135, v135
	v_sin_f32_e32 v131, v131
	v_pk_mul_f32 v[138:139], v[188:189], v[128:129] op_sel_hi:[0,1]
	v_pk_mul_f32 v[132:133], v[188:189], v[132:133] op_sel_hi:[0,1]
	v_pk_mul_f32 v[134:135], v[188:189], v[134:135] op_sel_hi:[0,1]
	v_pk_mul_f32 v[140:141], v[188:189], v[130:131] op_sel_hi:[0,1]
	v_pk_mul_f32 v[128:129], v[140:141], v[104:105]
	v_pk_mul_f32 v[130:131], v[134:135], v[106:107]
	v_pk_fma_f32 v[128:129], v[138:139], v[112:113], v[128:129] neg_lo:[0,0,1] neg_hi:[0,0,1]
	v_pk_fma_f32 v[130:131], v[132:133], v[114:115], v[130:131] neg_lo:[0,0,1] neg_hi:[0,0,1]
	v_pk_mul_f32 v[138:139], v[138:139], v[104:105]
	v_pk_mul_f32 v[132:133], v[132:133], v[106:107]
	s_nop 0
	v_pk_fma_f32 v[134:135], v[134:135], v[114:115], v[132:133]
	v_pk_fma_f32 v[132:133], v[140:141], v[112:113], v[138:139]
	s_cbranch_vccnz .LBB0_717
	v_pk_mul_f32 v[138:139], v[122:123], v[122:123]
	v_pk_mul_f32 v[140:141], v[120:121], v[120:121]
	s_nop 0
	v_pk_mov_b32 v[144:145], v[140:141], v[138:139] op_sel:[1,0]
	v_mov_b32_e32 v141, v139
	v_pk_add_f32 v[138:139], v[144:145], v[140:141]
	v_pk_mul_f32 v[140:141], v[130:131], v[130:131]
	v_pk_add_f32 v[138:139], v[138:139], v[138:139] op_sel_hi:[0,1]
	v_pk_mul_f32 v[144:145], v[128:129], v[128:129]
	v_mul_f32_e32 v138, v124, v124
	v_pk_mov_b32 v[146:147], v[144:145], v[140:141] op_sel:[1,0]
	v_mov_b32_e32 v145, v141
	v_pk_add_f32 v[140:141], v[146:147], v[144:145]
	v_pk_fma_f32 v[144:145], v[124:125], v[124:125], v[138:139] op_sel_hi:[1,1,0]
	v_mul_f32_e32 v138, v126, v126
	v_pk_add_f32 v[140:141], v[140:141], v[140:141] op_sel_hi:[0,1]
	v_pk_fma_f32 v[146:147], v[126:127], v[126:127], v[138:139] op_sel_hi:[1,1,0]
	v_mul_f32_e32 v144, v132, v132
	v_mul_f32_e32 v146, v133, v133
	v_mul_f32_e32 v138, v134, v134
	v_mul_f32_e32 v140, v135, v135
	v_pk_add_f32 v[144:145], v[144:145], v[146:147]
	v_pk_add_f32 v[138:139], v[138:139], v[140:141]
	v_and_b32_e32 v140, 64, v207
	v_pk_add_f32 v[138:139], v[144:145], v[138:139]
	v_add_u32_e32 v140, 64, v140
	v_add_f32_e32 v138, v138, v139
	v_xor_b32_e32 v139, 16, v207
	v_cmp_lt_i32_e32 vcc, v139, v140
	s_nop 1
	v_cndmask_b32_e32 v139, v207, v139, vcc
	v_lshlrev_b32_e32 v139, 2, v139
	ds_bpermute_b32 v139, v139, v138
	s_waitcnt lgkmcnt(0)
	v_add_f32_e32 v138, v138, v139
	v_xor_b32_e32 v139, 32, v207
	v_cmp_lt_i32_e32 vcc, v139, v140
	s_nop 1
	v_cndmask_b32_e32 v139, v207, v139, vcc
	v_lshlrev_b32_e32 v139, 2, v139
	ds_bpermute_b32 v139, v139, v138
	s_waitcnt lgkmcnt(0)
	v_add_f32_e32 v138, v138, v139
	v_max_f32_e32 v139, v158, v158
	v_max_f32_e32 v142, v139, v138

;     __device__ __forceinline__ void operator()(const f32x4 (&acc)[2][2][4][2], const Unit& u, int wr, int wc, int fr, int fq, PG8_LAS unsigned char* lds) const {
;     ...
;                 const int row = u.pm * BM + ai * HALF + wr * 64 + m * 16 + fr; const int t = row & tmask;
;                 const float rs = __builtin_amdgcn_rsqf((float)rss[row] * (2.3283064365386963e-10f / 1024.0f) + 1e-6f);
;                 f32x4 v[2][2];
; #pragma unroll
;                 for (int bj = 0; bj < 2; ++bj)
; #pragma unroll
;                     for (int n = 0; n < 2; ++n) v[bj][n] = acc[ai][bj][m][n] * rs;
;                 if (type <= 1) {
;                     float ss = 0.f;
; #pragma unroll
;                     for (int bj = 0; bj < 2; ++bj)
; #pragma unroll
;                         for (int n = 0; n < 2; ++n) { const f32x4 x = v[bj][n]; ss += (x[0] * x[0] + x[1] * x[1]) + (x[2] * x[2] + x[3] * x[3]); }
;                     ss += __shfl_xor(ss, 16); ss += __shfl_xor(ss, 32);
;                     float rn = __builtin_amdgcn_rsqf(ss * (1.0f / 64.0f) + 1e-6f); if (type == 0) rn *= QSCALE;
; #pragma unroll
;                     for (int bj = 0; bj < 2; ++bj) { const float pf = (float)(bj == 0 ? (t >> 6) : (t & 63)); f32x4 c, s;
; #pragma unroll
;                         for (int e = 0; e < 4; ++e) { const float a = __builtin_amdgcn_fractf(pf * f4[0][e]); c[e] = __builtin_amdgcn_cosf(a); s[e] = __builtin_amdgcn_sinf(a); }
;                         const f32x4 x1 = v[bj][0] * g[bj][0] * rn, x2 = v[bj][1] * g[bj][1] * rn;
;                         v[bj][0] = x1 * c - x2 * s; v[bj][1] = x1 * s + x2 * c; }
;                 } else if (type >= 3) {
;                     const float sc = type == 3 ? QSCALE : 1.0f; const float tf = (float)t;
; #pragma unroll
;                     for (int n = 0; n < 2; ++n) { f32x4 c, s;
; #pragma unroll
;                         for (int e = 0; e < 4; ++e) { const float a = __builtin_amdgcn_fractf(tf * f4[n][e]); c[e] = __builtin_amdgcn_cosf(a) * sc; s[e] = __builtin_amdgcn_sinf(a) * sc; }
;                         const f32x4 x1 = v[0][n], x2 = v[1][n];
;                         v[0][n] = x1 * c - x2 * s; v[1][n] = x1 * s + x2 * c; }
;                     if (type == 4) { float ks = 0.f;
; #pragma unroll
;                         for (int bj = 0; bj < 2; ++bj)
; #pragma unroll
.LBB0_720:
	v_lshl_add_u64 v[104:105], s[80:81], 0, v[136:137]
	v_lshlrev_b64 v[104:105], 7, v[104:105]
	v_lshl_add_u64 v[108:109], v[176:177], 0, v[104:105]
	v_cvt_pk_bf16_f32 v104, v120, v121
	v_cvt_pk_bf16_f32 v105, v122, v123
	v_cvt_pk_bf16_f32 v106, v128, v129
	v_cvt_pk_bf16_f32 v107, v130, v131
	v_add_u32_e32 v120, s67, v198
	v_permlane16_swap_b32_e32 v104, v106
	v_permlane16_swap_b32_e32 v105, v107
	global_store_dwordx4 v[108:109], v[104:107], off nt
	v_ashrrev_i32_e32 v121, 31, v120
	s_and_b64 vcc, exec, s[12:13]
	v_cvt_pk_bf16_f32 v104, v124, v125
	v_cvt_pk_bf16_f32 v105, v126, v127
	v_cvt_pk_bf16_f32 v106, v132, v133
	v_cvt_pk_bf16_f32 v107, v134, v135
	v_and_b32_e32 v127, s69, v120
	v_permlane16_swap_b32_e32 v104, v106
	v_permlane16_swap_b32_e32 v105, v107
	global_store_dwordx4 v[108:109], v[104:107], off offset:64 nt
	s_mov_b64 s[82:83], -1
	s_nop 0
	s_waitcnt vmcnt(6)
	v_mov_b64_e32 v[104:105], v[228:229]
	v_ffbh_u32_e32 v106, v105
	v_min_u32_e32 v106, 32, v106
	v_lshlrev_b64 v[104:105], v106, v[104:105]
	v_min_u32_e32 v104, 1, v104
	v_or_b32_e32 v104, v105, v104
	v_cvt_f32_u32_e32 v104, v104
	v_sub_u32_e32 v105, 32, v106
	v_ldexp_f32 v104, v104, v105
	v_fmamk_f32 v104, v104, 0x2a800000, v204
	v_rsq_f32_e32 v104, v104
	s_nop 0
	v_pk_mul_f32 v[102:103], v[102:103], v[104:105] op_sel_hi:[1,0]
	v_pk_mul_f32 v[100:101], v[100:101], v[104:105] op_sel_hi:[1,0]
	v_pk_mul_f32 v[98:99], v[98:99], v[104:105] op_sel_hi:[1,0]
	v_pk_mul_f32 v[96:97], v[96:97], v[104:105] op_sel_hi:[1,0]
	v_pk_mul_f32 v[94:95], v[94:95], v[104:105] op_sel_hi:[1,0]
	v_pk_mul_f32 v[92:93], v[92:93], v[104:105] op_sel_hi:[1,0]
	v_pk_mul_f32 v[90:91], v[90:91], v[104:105] op_sel_hi:[1,0]
	v_pk_mul_f32 v[88:89], v[88:89], v[104:105] op_sel_hi:[1,0]
	s_cbranch_vccnz .LBB0_725
	v_mov_b64_e32 v[106:107], v[102:103]
	v_mov_b64_e32 v[114:115], v[98:99]
	v_mov_b64_e32 v[110:111], v[94:95]
	v_mov_b64_e32 v[118:119], v[90:91]
	s_and_b64 vcc, exec, s[10:11]
	v_mov_b32_e32 v126, v142
	v_mov_b64_e32 v[104:105], v[100:101]
	v_mov_b64_e32 v[112:113], v[96:97]
	v_mov_b64_e32 v[108:109], v[92:93]
	v_mov_b64_e32 v[116:117], v[88:89]
	s_cbranch_vccnz .LBB0_724
	v_cvt_f32_u32_e32 v117, v127
	s_andn2_b64 vcc, exec, s[78:79]
	v_mov_b32_e32 v126, v142
	v_mul_f32_e32 v108, v30, v117
	v_fract_f32_e32 v109, v108
	v_mul_f32_e32 v104, v28, v117
	v_mul_f32_e32 v105, v29, v117
	v_cos_f32_e32 v108, v109
	v_sin_f32_e32 v110, v109
	v_mul_f32_e32 v109, v31, v117
	v_fract_f32_e32 v106, v104
	v_fract_f32_e32 v107, v105
	v_fract_f32_e32 v111, v109
	v_cos_f32_e32 v104, v106
	v_sin_f32_e32 v106, v106
	v_cos_f32_e32 v105, v107
	v_cos_f32_e32 v109, v111
	v_sin_f32_e32 v111, v111
	v_sin_f32_e32 v107, v107
	v_pk_mul_f32 v[112:113], v[188:189], v[104:105] op_sel_hi:[0,1]
	v_pk_mul_f32 v[108:109], v[188:189], v[108:109] op_sel_hi:[0,1]
	v_pk_mul_f32 v[110:111], v[188:189], v[110:111] op_sel_hi:[0,1]
	v_pk_mul_f32 v[114:115], v[188:189], v[106:107] op_sel_hi:[0,1]
	v_pk_mul_f32 v[104:105], v[114:115], v[92:93]
	v_pk_mul_f32 v[106:107], v[110:111], v[94:95]
	v_pk_fma_f32 v[104:105], v[112:113], v[100:101], v[104:105] neg_lo:[0,0,1] neg_hi:[0,0,1]
	v_pk_fma_f32 v[106:107], v[108:109], v[102:103], v[106:107] neg_lo:[0,0,1] neg_hi:[0,0,1]
	v_pk_mul_f32 v[112:113], v[112:113], v[92:93]
	v_pk_mul_f32 v[108:109], v[108:109], v[94:95]
	v_mul_f32_e32 v116, v54, v117
	v_pk_fma_f32 v[110:111], v[110:111], v[102:103], v[108:109]
	v_pk_fma_f32 v[108:109], v[114:115], v[100:101], v[112:113]
	v_mul_f32_e32 v112, v52, v117
	v_fract_f32_e32 v113, v112
	v_cos_f32_e32 v112, v113
	v_sin_f32_e32 v114, v113
	v_mul_f32_e32 v113, v53, v117
	v_mul_f32_e32 v117, v55, v117
	v_fract_f32_e32 v115, v113
	v_fract_f32_e32 v118, v116
	v_fract_f32_e32 v119, v117
	v_cos_f32_e32 v113, v115
	v_cos_f32_e32 v116, v118
	v_sin_f32_e32 v118, v118
	v_cos_f32_e32 v117, v119
	v_sin_f32_e32 v119, v119
	v_sin_f32_e32 v115, v115
	v_pk_mul_f32 v[122:123], v[188:189], v[112:113] op_sel_hi:[0,1]
	v_pk_mul_f32 v[116:117], v[188:189], v[116:117] op_sel_hi:[0,1]
	v_pk_mul_f32 v[118:119], v[188:189], v[118:119] op_sel_hi:[0,1]
	v_pk_mul_f32 v[124:125], v[188:189], v[114:115] op_sel_hi:[0,1]
	v_pk_mul_f32 v[112:113], v[124:125], v[88:89]
	v_pk_mul_f32 v[114:115], v[118:119], v[90:91]
	v_pk_fma_f32 v[112:113], v[122:123], v[96:97], v[112:113] neg_lo:[0,0,1] neg_hi:[0,0,1]
	v_pk_fma_f32 v[114:115], v[116:117], v[98:99], v[114:115] neg_lo:[0,0,1] neg_hi:[0,0,1]
	v_pk_mul_f32 v[122:123], v[122:123], v[88:89]
	v_pk_mul_f32 v[116:117], v[116:117], v[90:91]
	s_nop 0
	v_pk_fma_f32 v[118:119], v[118:119], v[98:99], v[116:117]
	v_pk_fma_f32 v[116:117], v[124:125], v[96:97], v[122:123]
	s_cbranch_vccnz .LBB0_724
	v_pk_mul_f32 v[122:123], v[106:107], v[106:107]
	v_pk_mul_f32 v[124:125], v[104:105], v[104:105]
	s_nop 0
	v_pk_mov_b32 v[128:129], v[124:125], v[122:123] op_sel:[1,0]
	v_mov_b32_e32 v125, v123
	v_pk_add_f32 v[122:123], v[128:129], v[124:125]
	v_pk_mul_f32 v[124:125], v[114:115], v[114:115]
	v_pk_add_f32 v[122:123], v[122:123], v[122:123] op_sel_hi:[0,1]
	v_pk_mul_f32 v[128:129], v[112:113], v[112:113]
	v_mul_f32_e32 v122, v108, v108
	v_pk_mov_b32 v[130:131], v[128:129], v[124:125] op_sel:[1,0]
	v_mov_b32_e32 v129, v125
	v_pk_add_f32 v[124:125], v[130:131], v[128:129]
	v_pk_fma_f32 v[128:129], v[108:109], v[108:109], v[122:123] op_sel_hi:[1,1,0]
	v_mul_f32_e32 v122, v110, v110
	v_pk_add_f32 v[124:125], v[124:125], v[124:125] op_sel_hi:[0,1]
	v_pk_fma_f32 v[130:131], v[110:111], v[110:111], v[122:123] op_sel_hi:[1,1,0]
	v_mul_f32_e32 v128, v116, v116
	v_mul_f32_e32 v130, v117, v117
	v_mul_f32_e32 v122, v118, v118
	v_mul_f32_e32 v124, v119, v119
	v_pk_add_f32 v[128:129], v[128:129], v[130:131]
	v_pk_add_f32 v[122:123], v[122:123], v[124:125]
	v_and_b32_e32 v124, 64, v207
	v_pk_add_f32 v[122:123], v[128:129], v[122:123]
	v_add_u32_e32 v124, 64, v124
	v_add_f32_e32 v122, v122, v123
	v_xor_b32_e32 v123, 16, v207
	v_cmp_lt_i32_e32 vcc, v123, v124
	s_nop 1
	v_cndmask_b32_e32 v123, v207, v123, vcc
	v_lshlrev_b32_e32 v123, 2, v123
	ds_bpermute_b32 v123, v123, v122
	s_waitcnt lgkmcnt(0)
	v_add_f32_e32 v122, v122, v123
	v_xor_b32_e32 v123, 32, v207
	v_cmp_lt_i32_e32 vcc, v123, v124
	s_nop 1
	v_cndmask_b32_e32 v123, v207, v123, vcc
	v_lshlrev_b32_e32 v123, 2, v123
	ds_bpermute_b32 v123, v123, v122
	s_waitcnt lgkmcnt(0)
	v_add_f32_e32 v122, v122, v123
	v_max_f32_e32 v123, v142, v142
	v_max_f32_e32 v126, v123, v122

;     __device__ __forceinline__ void operator()(const f32x4 (&acc)[2][2][4][2], const Unit& u, int wr, int wc, int fr, int fq, PG8_LAS unsigned char* lds) const {
;     ...
;                 const int row = u.pm * BM + ai * HALF + wr * 64 + m * 16 + fr; const int t = row & tmask;
;                 const float rs = __builtin_amdgcn_rsqf((float)rss[row] * (2.3283064365386963e-10f / 1024.0f) + 1e-6f);
;                 f32x4 v[2][2];
; #pragma unroll
;                 for (int bj = 0; bj < 2; ++bj)
; #pragma unroll
;                     for (int n = 0; n < 2; ++n) v[bj][n] = acc[ai][bj][m][n] * rs;
;                 if (type <= 1) {
;                     float ss = 0.f;
; #pragma unroll
;                     for (int bj = 0; bj < 2; ++bj)
; #pragma unroll
;                         for (int n = 0; n < 2; ++n) { const f32x4 x = v[bj][n]; ss += (x[0] * x[0] + x[1] * x[1]) + (x[2] * x[2] + x[3] * x[3]); }
;                     ss += __shfl_xor(ss, 16); ss += __shfl_xor(ss, 32);
;                     float rn = __builtin_amdgcn_rsqf(ss * (1.0f / 64.0f) + 1e-6f); if (type == 0) rn *= QSCALE;
; #pragma unroll
;                     for (int bj = 0; bj < 2; ++bj) { const float pf = (float)(bj == 0 ? (t >> 6) : (t & 63)); f32x4 c, s;
; #pragma unroll
;                         for (int e = 0; e < 4; ++e) { const float a = __builtin_amdgcn_fractf(pf * f4[0][e]); c[e] = __builtin_amdgcn_cosf(a); s[e] = __builtin_amdgcn_sinf(a); }
;                         const f32x4 x1 = v[bj][0] * g[bj][0] * rn, x2 = v[bj][1] * g[bj][1] * rn;
;                         v[bj][0] = x1 * c - x2 * s; v[bj][1] = x1 * s + x2 * c; }
;                 } else if (type >= 3) {
;                     const float sc = type == 3 ? QSCALE : 1.0f; const float tf = (float)t;
; #pragma unroll
;                     for (int n = 0; n < 2; ++n) { f32x4 c, s;
; #pragma unroll
;                         for (int e = 0; e < 4; ++e) { const float a = __builtin_amdgcn_fractf(tf * f4[n][e]); c[e] = __builtin_amdgcn_cosf(a) * sc; s[e] = __builtin_amdgcn_sinf(a) * sc; }
;                         const f32x4 x1 = v[0][n], x2 = v[1][n];
;                         v[0][n] = x1 * c - x2 * s; v[1][n] = x1 * s + x2 * c; }
;                     if (type == 4) { float ks = 0.f;
; #pragma unroll
;                         for (int bj = 0; bj < 2; ++bj)
; #pragma unroll
.LBB0_727:
	v_lshl_add_u64 v[88:89], s[80:81], 0, v[120:121]
	v_lshlrev_b64 v[88:89], 7, v[88:89]
	v_lshl_add_u64 v[92:93], v[176:177], 0, v[88:89]
	v_cvt_pk_bf16_f32 v88, v104, v105
	v_cvt_pk_bf16_f32 v89, v106, v107
	v_cvt_pk_bf16_f32 v90, v112, v113
	v_cvt_pk_bf16_f32 v91, v114, v115
	v_add_u32_e32 v104, 0x80, v190
	v_permlane16_swap_b32_e32 v88, v90
	v_permlane16_swap_b32_e32 v89, v91
	global_store_dwordx4 v[92:93], v[88:91], off nt
	v_ashrrev_i32_e32 v105, 31, v104
	s_and_b64 vcc, exec, s[12:13]
	v_cvt_pk_bf16_f32 v88, v108, v109
	v_cvt_pk_bf16_f32 v89, v110, v111
	v_cvt_pk_bf16_f32 v90, v116, v117
	v_cvt_pk_bf16_f32 v91, v118, v119
	v_and_b32_e32 v107, s69, v104
	v_permlane16_swap_b32_e32 v88, v90
	v_permlane16_swap_b32_e32 v89, v91
	global_store_dwordx4 v[92:93], v[88:91], off offset:64 nt
	s_mov_b64 s[82:83], -1
	s_nop 0
	s_waitcnt vmcnt(8)
	v_mov_b64_e32 v[88:89], v[230:231]
	v_ffbh_u32_e32 v90, v89
	v_min_u32_e32 v90, 32, v90
	v_lshlrev_b64 v[88:89], v90, v[88:89]
	v_min_u32_e32 v88, 1, v88
	v_or_b32_e32 v88, v89, v88
	v_cvt_f32_u32_e32 v88, v88
	v_sub_u32_e32 v89, 32, v90
	v_ldexp_f32 v88, v88, v89
	v_fmamk_f32 v88, v88, 0x2a800000, v204
	v_rsq_f32_e32 v88, v88
	s_nop 0
	v_pk_mul_f32 v[86:87], v[86:87], v[88:89] op_sel_hi:[1,0]
	v_pk_mul_f32 v[84:85], v[84:85], v[88:89] op_sel_hi:[1,0]
	v_pk_mul_f32 v[82:83], v[82:83], v[88:89] op_sel_hi:[1,0]
	v_pk_mul_f32 v[80:81], v[80:81], v[88:89] op_sel_hi:[1,0]
	v_pk_mul_f32 v[78:79], v[78:79], v[88:89] op_sel_hi:[1,0]
	v_pk_mul_f32 v[76:77], v[76:77], v[88:89] op_sel_hi:[1,0]
	v_pk_mul_f32 v[74:75], v[74:75], v[88:89] op_sel_hi:[1,0]
	v_pk_mul_f32 v[72:73], v[72:73], v[88:89] op_sel_hi:[1,0]
	s_cbranch_vccnz .LBB0_732
	v_mov_b64_e32 v[90:91], v[86:87]
	v_mov_b64_e32 v[98:99], v[82:83]
	v_mov_b64_e32 v[94:95], v[78:79]
	v_mov_b64_e32 v[102:103], v[74:75]
	s_and_b64 vcc, exec, s[10:11]
	v_mov_b32_e32 v106, v126
	v_mov_b64_e32 v[88:89], v[84:85]
	v_mov_b64_e32 v[96:97], v[80:81]
	v_mov_b64_e32 v[92:93], v[76:77]
	v_mov_b64_e32 v[100:101], v[72:73]
	s_cbranch_vccnz .LBB0_731
	v_cvt_f32_u32_e32 v101, v107
	s_andn2_b64 vcc, exec, s[78:79]
	v_mov_b32_e32 v106, v126
	v_mul_f32_e32 v92, v30, v101
	v_fract_f32_e32 v93, v92
	v_mul_f32_e32 v88, v28, v101
	v_mul_f32_e32 v89, v29, v101
	v_cos_f32_e32 v92, v93
	v_sin_f32_e32 v94, v93
	v_mul_f32_e32 v93, v31, v101
	v_fract_f32_e32 v90, v88
	v_fract_f32_e32 v91, v89
	v_fract_f32_e32 v95, v93
	v_cos_f32_e32 v88, v90
	v_sin_f32_e32 v90, v90
	v_cos_f32_e32 v89, v91
	v_cos_f32_e32 v93, v95
	v_sin_f32_e32 v95, v95
	v_sin_f32_e32 v91, v91
	v_pk_mul_f32 v[96:97], v[188:189], v[88:89] op_sel_hi:[0,1]
	v_pk_mul_f32 v[92:93], v[188:189], v[92:93] op_sel_hi:[0,1]
	v_pk_mul_f32 v[94:95], v[188:189], v[94:95] op_sel_hi:[0,1]
	v_pk_mul_f32 v[98:99], v[188:189], v[90:91] op_sel_hi:[0,1]
	v_pk_mul_f32 v[88:89], v[98:99], v[76:77]
	v_pk_mul_f32 v[90:91], v[94:95], v[78:79]
	v_pk_fma_f32 v[88:89], v[96:97], v[84:85], v[88:89] neg_lo:[0,0,1] neg_hi:[0,0,1]
	v_pk_fma_f32 v[90:91], v[92:93], v[86:87], v[90:91] neg_lo:[0,0,1] neg_hi:[0,0,1]
	v_pk_mul_f32 v[96:97], v[96:97], v[76:77]
	v_pk_mul_f32 v[92:93], v[92:93], v[78:79]
	v_mul_f32_e32 v100, v54, v101
	v_pk_fma_f32 v[94:95], v[94:95], v[86:87], v[92:93]
	v_pk_fma_f32 v[92:93], v[98:99], v[84:85], v[96:97]
	v_mul_f32_e32 v96, v52, v101
	v_fract_f32_e32 v97, v96
	v_cos_f32_e32 v96, v97
	v_sin_f32_e32 v98, v97
	v_mul_f32_e32 v97, v53, v101
	v_mul_f32_e32 v101, v55, v101
	v_fract_f32_e32 v99, v97
	v_fract_f32_e32 v102, v100
	v_fract_f32_e32 v103, v101
	v_cos_f32_e32 v97, v99
	v_cos_f32_e32 v100, v102
	v_sin_f32_e32 v102, v102
	v_cos_f32_e32 v101, v103
	v_sin_f32_e32 v103, v103
	v_sin_f32_e32 v99, v99
	v_pk_mul_f32 v[108:109], v[188:189], v[96:97] op_sel_hi:[0,1]
	v_pk_mul_f32 v[100:101], v[188:189], v[100:101] op_sel_hi:[0,1]
	v_pk_mul_f32 v[102:103], v[188:189], v[102:103] op_sel_hi:[0,1]
	v_pk_mul_f32 v[110:111], v[188:189], v[98:99] op_sel_hi:[0,1]
	v_pk_mul_f32 v[96:97], v[110:111], v[72:73]
	v_pk_mul_f32 v[98:99], v[102:103], v[74:75]
	v_pk_fma_f32 v[96:97], v[108:109], v[80:81], v[96:97] neg_lo:[0,0,1] neg_hi:[0,0,1]
	v_pk_fma_f32 v[98:99], v[100:101], v[82:83], v[98:99] neg_lo:[0,0,1] neg_hi:[0,0,1]
	v_pk_mul_f32 v[108:109], v[108:109], v[72:73]
	v_pk_mul_f32 v[100:101], v[100:101], v[74:75]
	s_nop 0
	v_pk_fma_f32 v[102:103], v[102:103], v[82:83], v[100:101]
	v_pk_fma_f32 v[100:101], v[110:111], v[80:81], v[108:109]
	s_cbranch_vccnz .LBB0_731
	v_pk_mul_f32 v[108:109], v[90:91], v[90:91]
	v_pk_mul_f32 v[110:111], v[88:89], v[88:89]
	v_mul_f32_e32 v106, v92, v92
	v_pk_mov_b32 v[112:113], v[110:111], v[108:109] op_sel:[1,0]
	v_mov_b32_e32 v111, v109
	v_pk_add_f32 v[108:109], v[112:113], v[110:111]
	v_pk_mul_f32 v[110:111], v[98:99], v[98:99]
	v_pk_mul_f32 v[112:113], v[96:97], v[96:97]
	v_pk_add_f32 v[108:109], v[108:109], v[108:109] op_sel_hi:[0,1]
	v_pk_mov_b32 v[114:115], v[112:113], v[110:111] op_sel:[1,0]
	v_mov_b32_e32 v113, v111
	v_pk_add_f32 v[110:111], v[114:115], v[112:113]
	v_pk_fma_f32 v[112:113], v[92:93], v[92:93], v[106:107] op_sel_hi:[1,1,0]
	v_mul_f32_e32 v106, v94, v94
	v_pk_add_f32 v[110:111], v[110:111], v[110:111] op_sel_hi:[0,1]
	v_pk_fma_f32 v[114:115], v[94:95], v[94:95], v[106:107] op_sel_hi:[1,1,0]
	v_mul_f32_e32 v112, v100, v100
	v_mul_f32_e32 v114, v101, v101
	v_mul_f32_e32 v108, v102, v102
	v_mul_f32_e32 v110, v103, v103
	v_pk_add_f32 v[112:113], v[112:113], v[114:115]
	v_pk_add_f32 v[108:109], v[108:109], v[110:111]
	s_nop 0
	v_pk_add_f32 v[108:109], v[112:113], v[108:109]
	s_nop 0
	v_add_f32_e32 v106, v108, v109
	v_and_b32_e32 v109, 64, v207
	v_xor_b32_e32 v108, 16, v207
	v_add_u32_e32 v109, 64, v109
	v_cmp_lt_i32_e32 vcc, v108, v109
	s_nop 1
	v_cndmask_b32_e32 v108, v207, v108, vcc
	v_lshlrev_b32_e32 v108, 2, v108
	ds_bpermute_b32 v108, v108, v106
	s_waitcnt lgkmcnt(0)
	v_add_f32_e32 v106, v106, v108
	v_xor_b32_e32 v108, 32, v207
	v_cmp_lt_i32_e32 vcc, v108, v109
	s_nop 1
	v_cndmask_b32_e32 v108, v207, v108, vcc
	v_lshlrev_b32_e32 v108, 2, v108
	ds_bpermute_b32 v108, v108, v106
	s_waitcnt lgkmcnt(0)
	v_add_f32_e32 v106, v106, v108
	v_max_f32_e32 v108, v126, v126
	v_max_f32_e32 v106, v108, v106

;     __device__ __forceinline__ void operator()(const f32x4 (&acc)[2][2][4][2], const Unit& u, int wr, int wc, int fr, int fq, PG8_LAS unsigned char* lds) const {
;     ...
;                 const int row = u.pm * BM + ai * HALF + wr * 64 + m * 16 + fr; const int t = row & tmask;
;                 const float rs = __builtin_amdgcn_rsqf((float)rss[row] * (2.3283064365386963e-10f / 1024.0f) + 1e-6f);
;                 f32x4 v[2][2];
; #pragma unroll
;                 for (int bj = 0; bj < 2; ++bj)
; #pragma unroll
;                     for (int n = 0; n < 2; ++n) v[bj][n] = acc[ai][bj][m][n] * rs;
;                 if (type <= 1) {
;                     float ss = 0.f;
; #pragma unroll
;                     for (int bj = 0; bj < 2; ++bj)
; #pragma unroll
;                         for (int n = 0; n < 2; ++n) { const f32x4 x = v[bj][n]; ss += (x[0] * x[0] + x[1] * x[1]) + (x[2] * x[2] + x[3] * x[3]); }
;                     ss += __shfl_xor(ss, 16); ss += __shfl_xor(ss, 32);
;                     float rn = __builtin_amdgcn_rsqf(ss * (1.0f / 64.0f) + 1e-6f); if (type == 0) rn *= QSCALE;
; #pragma unroll
;                     for (int bj = 0; bj < 2; ++bj) { const float pf = (float)(bj == 0 ? (t >> 6) : (t & 63)); f32x4 c, s;
; #pragma unroll
;                         for (int e = 0; e < 4; ++e) { const float a = __builtin_amdgcn_fractf(pf * f4[0][e]); c[e] = __builtin_amdgcn_cosf(a); s[e] = __builtin_amdgcn_sinf(a); }
;                         const f32x4 x1 = v[bj][0] * g[bj][0] * rn, x2 = v[bj][1] * g[bj][1] * rn;
;                         v[bj][0] = x1 * c - x2 * s; v[bj][1] = x1 * s + x2 * c; }
;                 } else if (type >= 3) {
;                     const float sc = type == 3 ? QSCALE : 1.0f; const float tf = (float)t;
; #pragma unroll
;                     for (int n = 0; n < 2; ++n) { f32x4 c, s;
; #pragma unroll
;                         for (int e = 0; e < 4; ++e) { const float a = __builtin_amdgcn_fractf(tf * f4[n][e]); c[e] = __builtin_amdgcn_cosf(a) * sc; s[e] = __builtin_amdgcn_sinf(a) * sc; }
;                         const f32x4 x1 = v[0][n], x2 = v[1][n];
;                         v[0][n] = x1 * c - x2 * s; v[1][n] = x1 * s + x2 * c; }
;                     if (type == 4) { float ks = 0.f;
; #pragma unroll
;                         for (int bj = 0; bj < 2; ++bj)
; #pragma unroll
.LBB0_734:
	v_lshl_add_u64 v[72:73], s[80:81], 0, v[104:105]
	v_lshlrev_b64 v[72:73], 7, v[72:73]
	v_lshl_add_u64 v[76:77], v[176:177], 0, v[72:73]
	v_cvt_pk_bf16_f32 v72, v88, v89
	v_cvt_pk_bf16_f32 v73, v90, v91
	v_cvt_pk_bf16_f32 v74, v96, v97
	v_cvt_pk_bf16_f32 v75, v98, v99
	v_add_u32_e32 v88, 0x90, v190
	v_permlane16_swap_b32_e32 v72, v74
	v_permlane16_swap_b32_e32 v73, v75
	global_store_dwordx4 v[76:77], v[72:75], off nt
	v_ashrrev_i32_e32 v89, 31, v88
	s_and_b64 vcc, exec, s[12:13]
	v_cvt_pk_bf16_f32 v72, v92, v93
	v_cvt_pk_bf16_f32 v73, v94, v95
	v_cvt_pk_bf16_f32 v74, v100, v101
	v_cvt_pk_bf16_f32 v75, v102, v103
	v_and_b32_e32 v91, s69, v88
	v_permlane16_swap_b32_e32 v72, v74
	v_permlane16_swap_b32_e32 v73, v75
	global_store_dwordx4 v[76:77], v[72:75], off offset:64 nt
	s_mov_b64 s[82:83], -1
	s_nop 0
	s_waitcnt vmcnt(10)
	v_mov_b64_e32 v[72:73], v[232:233]
	v_ffbh_u32_e32 v74, v73
	v_min_u32_e32 v74, 32, v74
	v_lshlrev_b64 v[72:73], v74, v[72:73]
	v_min_u32_e32 v72, 1, v72
	v_or_b32_e32 v72, v73, v72
	v_cvt_f32_u32_e32 v72, v72
	v_sub_u32_e32 v73, 32, v74
	v_ldexp_f32 v72, v72, v73
	v_fmamk_f32 v72, v72, 0x2a800000, v204
	v_rsq_f32_e32 v72, v72
	s_nop 0
	v_pk_mul_f32 v[70:71], v[70:71], v[72:73] op_sel_hi:[1,0]
	v_pk_mul_f32 v[68:69], v[68:69], v[72:73] op_sel_hi:[1,0]
	v_pk_mul_f32 v[66:67], v[66:67], v[72:73] op_sel_hi:[1,0]
	v_pk_mul_f32 v[64:65], v[64:65], v[72:73] op_sel_hi:[1,0]
	v_pk_mul_f32 v[62:63], v[62:63], v[72:73] op_sel_hi:[1,0]
	v_pk_mul_f32 v[60:61], v[60:61], v[72:73] op_sel_hi:[1,0]
	v_pk_mul_f32 v[58:59], v[58:59], v[72:73] op_sel_hi:[1,0]
	v_pk_mul_f32 v[56:57], v[56:57], v[72:73] op_sel_hi:[1,0]
	s_cbranch_vccnz .LBB0_739
	v_mov_b64_e32 v[74:75], v[70:71]
	v_mov_b64_e32 v[82:83], v[66:67]
	v_mov_b64_e32 v[78:79], v[62:63]
	v_mov_b64_e32 v[86:87], v[58:59]
	s_and_b64 vcc, exec, s[10:11]
	v_mov_b32_e32 v90, v106
	v_mov_b64_e32 v[72:73], v[68:69]
	v_mov_b64_e32 v[80:81], v[64:65]
	v_mov_b64_e32 v[76:77], v[60:61]
	v_mov_b64_e32 v[84:85], v[56:57]
	s_cbranch_vccnz .LBB0_738
	v_cvt_f32_u32_e32 v85, v91
	s_andn2_b64 vcc, exec, s[78:79]
	v_mov_b32_e32 v90, v106
	v_mul_f32_e32 v76, v30, v85
	v_fract_f32_e32 v77, v76
	v_mul_f32_e32 v72, v28, v85
	v_mul_f32_e32 v73, v29, v85
	v_cos_f32_e32 v76, v77
	v_sin_f32_e32 v78, v77
	v_mul_f32_e32 v77, v31, v85
	v_fract_f32_e32 v74, v72
	v_fract_f32_e32 v75, v73
	v_fract_f32_e32 v79, v77
	v_cos_f32_e32 v72, v74
	v_sin_f32_e32 v74, v74
	v_cos_f32_e32 v73, v75
	v_cos_f32_e32 v77, v79
	v_sin_f32_e32 v79, v79
	v_sin_f32_e32 v75, v75
	v_pk_mul_f32 v[80:81], v[188:189], v[72:73] op_sel_hi:[0,1]
	v_pk_mul_f32 v[76:77], v[188:189], v[76:77] op_sel_hi:[0,1]
	v_pk_mul_f32 v[78:79], v[188:189], v[78:79] op_sel_hi:[0,1]
	v_pk_mul_f32 v[82:83], v[188:189], v[74:75] op_sel_hi:[0,1]
	v_pk_mul_f32 v[72:73], v[82:83], v[60:61]
	v_pk_mul_f32 v[74:75], v[78:79], v[62:63]
	v_pk_fma_f32 v[72:73], v[80:81], v[68:69], v[72:73] neg_lo:[0,0,1] neg_hi:[0,0,1]
	v_pk_fma_f32 v[74:75], v[76:77], v[70:71], v[74:75] neg_lo:[0,0,1] neg_hi:[0,0,1]
	v_pk_mul_f32 v[80:81], v[80:81], v[60:61]
	v_pk_mul_f32 v[76:77], v[76:77], v[62:63]
	v_mul_f32_e32 v84, v54, v85
	v_pk_fma_f32 v[78:79], v[78:79], v[70:71], v[76:77]
	v_pk_fma_f32 v[76:77], v[82:83], v[68:69], v[80:81]
	v_mul_f32_e32 v80, v52, v85
	v_fract_f32_e32 v81, v80
	v_cos_f32_e32 v80, v81
	v_sin_f32_e32 v82, v81
	v_mul_f32_e32 v81, v53, v85
	v_mul_f32_e32 v85, v55, v85
	v_fract_f32_e32 v83, v81
	v_fract_f32_e32 v86, v84
	v_fract_f32_e32 v87, v85
	v_cos_f32_e32 v81, v83
	v_cos_f32_e32 v84, v86
	v_sin_f32_e32 v86, v86
	v_cos_f32_e32 v85, v87
	v_sin_f32_e32 v87, v87
	v_sin_f32_e32 v83, v83
	v_pk_mul_f32 v[92:93], v[188:189], v[80:81] op_sel_hi:[0,1]
	v_pk_mul_f32 v[84:85], v[188:189], v[84:85] op_sel_hi:[0,1]
	v_pk_mul_f32 v[86:87], v[188:189], v[86:87] op_sel_hi:[0,1]
	v_pk_mul_f32 v[94:95], v[188:189], v[82:83] op_sel_hi:[0,1]
	v_pk_mul_f32 v[80:81], v[94:95], v[56:57]
	v_pk_mul_f32 v[82:83], v[86:87], v[58:59]
	v_pk_fma_f32 v[80:81], v[92:93], v[64:65], v[80:81] neg_lo:[0,0,1] neg_hi:[0,0,1]
	v_pk_fma_f32 v[82:83], v[84:85], v[66:67], v[82:83] neg_lo:[0,0,1] neg_hi:[0,0,1]
	v_pk_mul_f32 v[92:93], v[92:93], v[56:57]
	v_pk_mul_f32 v[84:85], v[84:85], v[58:59]
	s_nop 0
	v_pk_fma_f32 v[86:87], v[86:87], v[66:67], v[84:85]
	v_pk_fma_f32 v[84:85], v[94:95], v[64:65], v[92:93]
	s_cbranch_vccnz .LBB0_738
	v_pk_mul_f32 v[92:93], v[74:75], v[74:75]
	v_pk_mul_f32 v[94:95], v[72:73], v[72:73]
	v_mul_f32_e32 v90, v76, v76
	v_pk_mov_b32 v[96:97], v[94:95], v[92:93] op_sel:[1,0]
	v_mov_b32_e32 v95, v93
	v_pk_add_f32 v[92:93], v[96:97], v[94:95]
	v_pk_mul_f32 v[94:95], v[82:83], v[82:83]
	v_pk_mul_f32 v[96:97], v[80:81], v[80:81]
	v_pk_add_f32 v[92:93], v[92:93], v[92:93] op_sel_hi:[0,1]
	v_pk_mov_b32 v[98:99], v[96:97], v[94:95] op_sel:[1,0]
	v_mov_b32_e32 v97, v95
	v_pk_add_f32 v[94:95], v[98:99], v[96:97]
	v_pk_fma_f32 v[96:97], v[76:77], v[76:77], v[90:91] op_sel_hi:[1,1,0]
	v_mul_f32_e32 v90, v78, v78
	v_pk_add_f32 v[94:95], v[94:95], v[94:95] op_sel_hi:[0,1]
	v_pk_fma_f32 v[98:99], v[78:79], v[78:79], v[90:91] op_sel_hi:[1,1,0]
	v_mul_f32_e32 v96, v84, v84
	v_mul_f32_e32 v98, v85, v85
	v_mul_f32_e32 v92, v86, v86
	v_mul_f32_e32 v94, v87, v87
	v_pk_add_f32 v[96:97], v[96:97], v[98:99]
	v_pk_add_f32 v[92:93], v[92:93], v[94:95]
	s_nop 0
	v_pk_add_f32 v[92:93], v[96:97], v[92:93]
	s_nop 0
	v_add_f32_e32 v90, v92, v93
	v_and_b32_e32 v93, 64, v207
	v_xor_b32_e32 v92, 16, v207
	v_add_u32_e32 v93, 64, v93
	v_cmp_lt_i32_e32 vcc, v92, v93
	s_nop 1
	v_cndmask_b32_e32 v92, v207, v92, vcc
	v_lshlrev_b32_e32 v92, 2, v92
	ds_bpermute_b32 v92, v92, v90
	s_waitcnt lgkmcnt(0)
	v_add_f32_e32 v90, v90, v92
	v_xor_b32_e32 v92, 32, v207
	v_cmp_lt_i32_e32 vcc, v92, v93
	s_nop 1
	v_cndmask_b32_e32 v92, v207, v92, vcc
	v_lshlrev_b32_e32 v92, 2, v92
	ds_bpermute_b32 v92, v92, v90
	s_waitcnt lgkmcnt(0)
	v_add_f32_e32 v90, v90, v92
	v_max_f32_e32 v92, v106, v106
	v_max_f32_e32 v90, v92, v90

;     __device__ __forceinline__ void operator()(const f32x4 (&acc)[2][2][4][2], const Unit& u, int wr, int wc, int fr, int fq, PG8_LAS unsigned char* lds) const {
;     ...
;                 const int row = u.pm * BM + ai * HALF + wr * 64 + m * 16 + fr; const int t = row & tmask;
;                 const float rs = __builtin_amdgcn_rsqf((float)rss[row] * (2.3283064365386963e-10f / 1024.0f) + 1e-6f);
;                 f32x4 v[2][2];
; #pragma unroll
;                 for (int bj = 0; bj < 2; ++bj)
; #pragma unroll
;                     for (int n = 0; n < 2; ++n) v[bj][n] = acc[ai][bj][m][n] * rs;
;                 if (type <= 1) {
;                     float ss = 0.f;
; #pragma unroll
;                     for (int bj = 0; bj < 2; ++bj)
; #pragma unroll
;                         for (int n = 0; n < 2; ++n) { const f32x4 x = v[bj][n]; ss += (x[0] * x[0] + x[1] * x[1]) + (x[2] * x[2] + x[3] * x[3]); }
;                     ss += __shfl_xor(ss, 16); ss += __shfl_xor(ss, 32);
;                     float rn = __builtin_amdgcn_rsqf(ss * (1.0f / 64.0f) + 1e-6f); if (type == 0) rn *= QSCALE;
; #pragma unroll
;                     for (int bj = 0; bj < 2; ++bj) { const float pf = (float)(bj == 0 ? (t >> 6) : (t & 63)); f32x4 c, s;
; #pragma unroll
;                         for (int e = 0; e < 4; ++e) { const float a = __builtin_amdgcn_fractf(pf * f4[0][e]); c[e] = __builtin_amdgcn_cosf(a); s[e] = __builtin_amdgcn_sinf(a); }
;                         const f32x4 x1 = v[bj][0] * g[bj][0] * rn, x2 = v[bj][1] * g[bj][1] * rn;
;                         v[bj][0] = x1 * c - x2 * s; v[bj][1] = x1 * s + x2 * c; }
;                 } else if (type >= 3) {
;                     const float sc = type == 3 ? QSCALE : 1.0f; const float tf = (float)t;
; #pragma unroll
;                     for (int n = 0; n < 2; ++n) { f32x4 c, s;
; #pragma unroll
;                         for (int e = 0; e < 4; ++e) { const float a = __builtin_amdgcn_fractf(tf * f4[n][e]); c[e] = __builtin_amdgcn_cosf(a) * sc; s[e] = __builtin_amdgcn_sinf(a) * sc; }
;                         const f32x4 x1 = v[0][n], x2 = v[1][n];
;                         v[0][n] = x1 * c - x2 * s; v[1][n] = x1 * s + x2 * c; }
;                     if (type == 4) { float ks = 0.f;
; #pragma unroll
;                         for (int bj = 0; bj < 2; ++bj)
; #pragma unroll
.LBB0_741:
	v_lshl_add_u64 v[56:57], s[80:81], 0, v[88:89]
	v_lshlrev_b64 v[56:57], 7, v[56:57]
	v_lshl_add_u64 v[60:61], v[176:177], 0, v[56:57]
	v_cvt_pk_bf16_f32 v56, v72, v73
	v_cvt_pk_bf16_f32 v57, v74, v75
	v_cvt_pk_bf16_f32 v58, v80, v81
	v_cvt_pk_bf16_f32 v59, v82, v83
	v_add_u32_e32 v72, 0xa0, v190
	v_permlane16_swap_b32_e32 v56, v58
	v_permlane16_swap_b32_e32 v57, v59
	global_store_dwordx4 v[60:61], v[56:59], off nt
	v_ashrrev_i32_e32 v73, 31, v72
	s_and_b64 vcc, exec, s[12:13]
	v_cvt_pk_bf16_f32 v56, v76, v77
	v_cvt_pk_bf16_f32 v57, v78, v79
	v_cvt_pk_bf16_f32 v58, v84, v85
	v_cvt_pk_bf16_f32 v59, v86, v87
	v_and_b32_e32 v75, s69, v72
	v_permlane16_swap_b32_e32 v56, v58
	v_permlane16_swap_b32_e32 v57, v59
	global_store_dwordx4 v[60:61], v[56:59], off offset:64 nt
	s_mov_b64 s[82:83], -1
	s_nop 0
	s_waitcnt vmcnt(12)
	v_mov_b64_e32 v[56:57], v[234:235]
	v_ffbh_u32_e32 v58, v57
	v_min_u32_e32 v58, 32, v58
	v_lshlrev_b64 v[56:57], v58, v[56:57]
	v_min_u32_e32 v56, 1, v56
	v_or_b32_e32 v56, v57, v56
	v_cvt_f32_u32_e32 v56, v56
	v_sub_u32_e32 v57, 32, v58
	v_ldexp_f32 v56, v56, v57
	v_fmamk_f32 v56, v56, 0x2a800000, v204
	v_rsq_f32_e32 v56, v56
	s_nop 0
	v_pk_mul_f32 v[34:35], v[34:35], v[56:57] op_sel_hi:[1,0]
	v_pk_mul_f32 v[32:33], v[32:33], v[56:57] op_sel_hi:[1,0]
	v_pk_mul_f32 v[26:27], v[26:27], v[56:57] op_sel_hi:[1,0]
	v_pk_mul_f32 v[24:25], v[24:25], v[56:57] op_sel_hi:[1,0]
	v_pk_mul_f32 v[22:23], v[22:23], v[56:57] op_sel_hi:[1,0]
	v_pk_mul_f32 v[20:21], v[20:21], v[56:57] op_sel_hi:[1,0]
	v_pk_mul_f32 v[18:19], v[18:19], v[56:57] op_sel_hi:[1,0]
	v_pk_mul_f32 v[16:17], v[16:17], v[56:57] op_sel_hi:[1,0]
	s_cbranch_vccnz .LBB0_746
	v_mov_b64_e32 v[58:59], v[34:35]
	v_mov_b64_e32 v[66:67], v[26:27]
	v_mov_b64_e32 v[62:63], v[22:23]
	v_mov_b64_e32 v[70:71], v[18:19]
	s_and_b64 vcc, exec, s[10:11]
	v_mov_b32_e32 v74, v90
	v_mov_b64_e32 v[56:57], v[32:33]
	v_mov_b64_e32 v[64:65], v[24:25]
	v_mov_b64_e32 v[60:61], v[20:21]
	v_mov_b64_e32 v[68:69], v[16:17]
	s_cbranch_vccnz .LBB0_745
	v_cvt_f32_u32_e32 v69, v75
	s_andn2_b64 vcc, exec, s[78:79]
	v_mov_b32_e32 v74, v90
	v_mul_f32_e32 v60, v30, v69
	v_fract_f32_e32 v61, v60
	v_mul_f32_e32 v56, v28, v69
	v_mul_f32_e32 v57, v29, v69
	v_cos_f32_e32 v60, v61
	v_sin_f32_e32 v62, v61
	v_mul_f32_e32 v61, v31, v69
	v_fract_f32_e32 v58, v56
	v_fract_f32_e32 v59, v57
	v_fract_f32_e32 v63, v61
	v_cos_f32_e32 v56, v58
	v_sin_f32_e32 v58, v58
	v_cos_f32_e32 v57, v59
	v_cos_f32_e32 v61, v63
	v_sin_f32_e32 v63, v63
	v_sin_f32_e32 v59, v59
	v_pk_mul_f32 v[64:65], v[188:189], v[56:57] op_sel_hi:[0,1]
	v_pk_mul_f32 v[60:61], v[188:189], v[60:61] op_sel_hi:[0,1]
	v_pk_mul_f32 v[62:63], v[188:189], v[62:63] op_sel_hi:[0,1]
	v_pk_mul_f32 v[66:67], v[188:189], v[58:59] op_sel_hi:[0,1]
	v_pk_mul_f32 v[56:57], v[66:67], v[20:21]
	v_pk_mul_f32 v[58:59], v[62:63], v[22:23]
	v_pk_fma_f32 v[56:57], v[64:65], v[32:33], v[56:57] neg_lo:[0,0,1] neg_hi:[0,0,1]
	v_pk_fma_f32 v[58:59], v[60:61], v[34:35], v[58:59] neg_lo:[0,0,1] neg_hi:[0,0,1]
	v_pk_mul_f32 v[64:65], v[64:65], v[20:21]
	v_pk_mul_f32 v[60:61], v[60:61], v[22:23]
	v_mul_f32_e32 v68, v54, v69
	v_pk_fma_f32 v[62:63], v[62:63], v[34:35], v[60:61]
	v_pk_fma_f32 v[60:61], v[66:67], v[32:33], v[64:65]
	v_mul_f32_e32 v64, v52, v69
	v_fract_f32_e32 v65, v64
	v_cos_f32_e32 v64, v65
	v_sin_f32_e32 v66, v65
	v_mul_f32_e32 v65, v53, v69
	v_mul_f32_e32 v69, v55, v69
	v_fract_f32_e32 v67, v65
	v_fract_f32_e32 v70, v68
	v_fract_f32_e32 v71, v69
	v_cos_f32_e32 v65, v67
	v_cos_f32_e32 v68, v70
	v_sin_f32_e32 v70, v70
	v_cos_f32_e32 v69, v71
	v_sin_f32_e32 v71, v71
	v_sin_f32_e32 v67, v67
	v_pk_mul_f32 v[76:77], v[188:189], v[64:65] op_sel_hi:[0,1]
	v_pk_mul_f32 v[68:69], v[188:189], v[68:69] op_sel_hi:[0,1]
	v_pk_mul_f32 v[70:71], v[188:189], v[70:71] op_sel_hi:[0,1]
	v_pk_mul_f32 v[78:79], v[188:189], v[66:67] op_sel_hi:[0,1]
	v_pk_mul_f32 v[64:65], v[78:79], v[16:17]
	v_pk_mul_f32 v[66:67], v[70:71], v[18:19]
	v_pk_fma_f32 v[64:65], v[76:77], v[24:25], v[64:65] neg_lo:[0,0,1] neg_hi:[0,0,1]
	v_pk_fma_f32 v[66:67], v[68:69], v[26:27], v[66:67] neg_lo:[0,0,1] neg_hi:[0,0,1]
	v_pk_mul_f32 v[76:77], v[76:77], v[16:17]
	v_pk_mul_f32 v[68:69], v[68:69], v[18:19]
	s_nop 0
	v_pk_fma_f32 v[70:71], v[70:71], v[26:27], v[68:69]
	v_pk_fma_f32 v[68:69], v[78:79], v[24:25], v[76:77]
	s_cbranch_vccnz .LBB0_745
	v_pk_mul_f32 v[76:77], v[58:59], v[58:59]
	v_pk_mul_f32 v[78:79], v[56:57], v[56:57]
	v_mul_f32_e32 v74, v60, v60
	v_pk_mov_b32 v[80:81], v[78:79], v[76:77] op_sel:[1,0]
	v_mov_b32_e32 v79, v77
	v_pk_add_f32 v[76:77], v[80:81], v[78:79]
	v_pk_mul_f32 v[78:79], v[66:67], v[66:67]
	v_pk_mul_f32 v[80:81], v[64:65], v[64:65]
	v_pk_add_f32 v[76:77], v[76:77], v[76:77] op_sel_hi:[0,1]
	v_pk_mov_b32 v[82:83], v[80:81], v[78:79] op_sel:[1,0]
	v_mov_b32_e32 v81, v79
	v_pk_add_f32 v[78:79], v[82:83], v[80:81]
	v_pk_fma_f32 v[80:81], v[60:61], v[60:61], v[74:75] op_sel_hi:[1,1,0]
	v_mul_f32_e32 v74, v62, v62
	v_pk_add_f32 v[78:79], v[78:79], v[78:79] op_sel_hi:[0,1]
	v_pk_fma_f32 v[82:83], v[62:63], v[62:63], v[74:75] op_sel_hi:[1,1,0]
	v_mul_f32_e32 v80, v68, v68
	v_mul_f32_e32 v82, v69, v69
	v_mul_f32_e32 v76, v70, v70
	v_mul_f32_e32 v78, v71, v71
	v_pk_add_f32 v[80:81], v[80:81], v[82:83]
	v_pk_add_f32 v[76:77], v[76:77], v[78:79]
	s_nop 0
	v_pk_add_f32 v[76:77], v[80:81], v[76:77]
	s_nop 0
	v_add_f32_e32 v74, v76, v77
	v_and_b32_e32 v77, 64, v207
	v_xor_b32_e32 v76, 16, v207
	v_add_u32_e32 v77, 64, v77
	v_cmp_lt_i32_e32 vcc, v76, v77
	s_nop 1
	v_cndmask_b32_e32 v76, v207, v76, vcc
	v_lshlrev_b32_e32 v76, 2, v76
	ds_bpermute_b32 v76, v76, v74
	s_waitcnt lgkmcnt(0)
	v_add_f32_e32 v74, v74, v76
	v_xor_b32_e32 v76, 32, v207
	v_cmp_lt_i32_e32 vcc, v76, v77
	s_nop 1
	v_cndmask_b32_e32 v76, v207, v76, vcc
	v_lshlrev_b32_e32 v76, 2, v76
	ds_bpermute_b32 v76, v76, v74
	s_waitcnt lgkmcnt(0)
	v_add_f32_e32 v74, v74, v76
	v_max_f32_e32 v76, v90, v90
	v_max_f32_e32 v74, v76, v74

;     __device__ __forceinline__ void operator()(const f32x4 (&acc)[2][2][4][2], const Unit& u, int wr, int wc, int fr, int fq, PG8_LAS unsigned char* lds) const {
;     ...
;                 const int row = u.pm * BM + ai * HALF + wr * 64 + m * 16 + fr; const int t = row & tmask;
;                 const float rs = __builtin_amdgcn_rsqf((float)rss[row] * (2.3283064365386963e-10f / 1024.0f) + 1e-6f);
;                 f32x4 v[2][2];
; #pragma unroll
;                 for (int bj = 0; bj < 2; ++bj)
; #pragma unroll
;                     for (int n = 0; n < 2; ++n) v[bj][n] = acc[ai][bj][m][n] * rs;
;                 if (type <= 1) {
;                     float ss = 0.f;
; #pragma unroll
;                     for (int bj = 0; bj < 2; ++bj)
; #pragma unroll
;                         for (int n = 0; n < 2; ++n) { const f32x4 x = v[bj][n]; ss += (x[0] * x[0] + x[1] * x[1]) + (x[2] * x[2] + x[3] * x[3]); }
;                     ss += __shfl_xor(ss, 16); ss += __shfl_xor(ss, 32);
;                     float rn = __builtin_amdgcn_rsqf(ss * (1.0f / 64.0f) + 1e-6f); if (type == 0) rn *= QSCALE;
; #pragma unroll
;                     for (int bj = 0; bj < 2; ++bj) { const float pf = (float)(bj == 0 ? (t >> 6) : (t & 63)); f32x4 c, s;
; #pragma unroll
;                         for (int e = 0; e < 4; ++e) { const float a = __builtin_amdgcn_fractf(pf * f4[0][e]); c[e] = __builtin_amdgcn_cosf(a); s[e] = __builtin_amdgcn_sinf(a); }
;                         const f32x4 x1 = v[bj][0] * g[bj][0] * rn, x2 = v[bj][1] * g[bj][1] * rn;
;                         v[bj][0] = x1 * c - x2 * s; v[bj][1] = x1 * s + x2 * c; }
;                 } else if (type >= 3) {
;                     const float sc = type == 3 ? QSCALE : 1.0f; const float tf = (float)t;
; #pragma unroll
;                     for (int n = 0; n < 2; ++n) { f32x4 c, s;
; #pragma unroll
;                         for (int e = 0; e < 4; ++e) { const float a = __builtin_amdgcn_fractf(tf * f4[n][e]); c[e] = __builtin_amdgcn_cosf(a) * sc; s[e] = __builtin_amdgcn_sinf(a) * sc; }
;                         const f32x4 x1 = v[0][n], x2 = v[1][n];
;                         v[0][n] = x1 * c - x2 * s; v[1][n] = x1 * s + x2 * c; }
;                     if (type == 4) { float ks = 0.f;
; #pragma unroll
;                         for (int bj = 0; bj < 2; ++bj)
; #pragma unroll
.LBB0_748:
	v_lshl_add_u64 v[16:17], s[80:81], 0, v[72:73]
	v_lshlrev_b64 v[16:17], 7, v[16:17]
	v_lshl_add_u64 v[20:21], v[176:177], 0, v[16:17]
	v_cvt_pk_bf16_f32 v16, v56, v57
	v_cvt_pk_bf16_f32 v17, v58, v59
	v_cvt_pk_bf16_f32 v18, v64, v65
	v_cvt_pk_bf16_f32 v19, v66, v67
	v_add_u32_e32 v56, 0xb0, v190
	v_permlane16_swap_b32_e32 v16, v18
	v_permlane16_swap_b32_e32 v17, v19
	global_store_dwordx4 v[20:21], v[16:19], off nt
	v_ashrrev_i32_e32 v57, 31, v56
	s_and_b64 vcc, exec, s[12:13]
	v_cvt_pk_bf16_f32 v16, v60, v61
	v_cvt_pk_bf16_f32 v17, v62, v63
	v_cvt_pk_bf16_f32 v18, v68, v69
	v_cvt_pk_bf16_f32 v19, v70, v71
	v_and_b32_e32 v58, s69, v56
	v_permlane16_swap_b32_e32 v16, v18
	v_permlane16_swap_b32_e32 v17, v19
	global_store_dwordx4 v[20:21], v[16:19], off offset:64 nt
	s_mov_b64 s[12:13], -1
	s_nop 0
	s_waitcnt vmcnt(14)
	v_mov_b64_e32 v[16:17], v[236:237]
	v_ffbh_u32_e32 v18, v17
	v_min_u32_e32 v18, 32, v18
	v_lshlrev_b64 v[16:17], v18, v[16:17]
	v_min_u32_e32 v16, 1, v16
	v_or_b32_e32 v16, v17, v16
	v_cvt_f32_u32_e32 v16, v16
	v_sub_u32_e32 v17, 32, v18
	v_ldexp_f32 v16, v16, v17
	v_fmamk_f32 v16, v16, 0x2a800000, v204
	v_rsq_f32_e32 v16, v16
	s_nop 0
	v_pk_mul_f32 v[14:15], v[14:15], v[16:17] op_sel_hi:[1,0]
	v_pk_mul_f32 v[12:13], v[12:13], v[16:17] op_sel_hi:[1,0]
	v_pk_mul_f32 v[10:11], v[10:11], v[16:17] op_sel_hi:[1,0]
	v_pk_mul_f32 v[8:9], v[8:9], v[16:17] op_sel_hi:[1,0]
	v_pk_mul_f32 v[6:7], v[6:7], v[16:17] op_sel_hi:[1,0]
	v_pk_mul_f32 v[4:5], v[4:5], v[16:17] op_sel_hi:[1,0]
	v_pk_mul_f32 v[2:3], v[2:3], v[16:17] op_sel_hi:[1,0]
	v_pk_mul_f32 v[0:1], v[0:1], v[16:17] op_sel_hi:[1,0]
	s_cbranch_vccnz .LBB0_753
	v_mov_b64_e32 v[18:19], v[14:15]
	v_mov_b64_e32 v[26:27], v[10:11]
	v_mov_b64_e32 v[22:23], v[6:7]
	v_mov_b64_e32 v[34:35], v[2:3]
	s_and_b64 vcc, exec, s[10:11]
	v_mov_b32_e32 v59, v74
	v_mov_b64_e32 v[16:17], v[12:13]
	v_mov_b64_e32 v[24:25], v[8:9]
	v_mov_b64_e32 v[20:21], v[4:5]
	v_mov_b64_e32 v[32:33], v[0:1]
	s_cbranch_vccnz .LBB0_752
	v_cvt_f32_u32_e32 v33, v58
	s_andn2_b64 vcc, exec, s[78:79]
	v_mov_b32_e32 v59, v74
	v_mul_f32_e32 v20, v30, v33
	v_fract_f32_e32 v21, v20
	v_mul_f32_e32 v16, v28, v33
	v_mul_f32_e32 v17, v29, v33
	v_cos_f32_e32 v20, v21
	v_sin_f32_e32 v22, v21
	v_mul_f32_e32 v21, v31, v33
	v_fract_f32_e32 v18, v16
	v_fract_f32_e32 v19, v17
	v_fract_f32_e32 v23, v21
	v_cos_f32_e32 v16, v18
	v_sin_f32_e32 v18, v18
	v_cos_f32_e32 v17, v19
	v_cos_f32_e32 v21, v23
	v_sin_f32_e32 v23, v23
	v_sin_f32_e32 v19, v19
	v_pk_mul_f32 v[24:25], v[188:189], v[16:17] op_sel_hi:[0,1]
	v_pk_mul_f32 v[20:21], v[188:189], v[20:21] op_sel_hi:[0,1]
	v_pk_mul_f32 v[22:23], v[188:189], v[22:23] op_sel_hi:[0,1]
	v_pk_mul_f32 v[26:27], v[188:189], v[18:19] op_sel_hi:[0,1]
	v_pk_mul_f32 v[16:17], v[26:27], v[4:5]
	v_pk_mul_f32 v[18:19], v[22:23], v[6:7]
	v_pk_fma_f32 v[16:17], v[24:25], v[12:13], v[16:17] neg_lo:[0,0,1] neg_hi:[0,0,1]
	v_pk_fma_f32 v[18:19], v[20:21], v[14:15], v[18:19] neg_lo:[0,0,1] neg_hi:[0,0,1]
	v_pk_mul_f32 v[24:25], v[24:25], v[4:5]
	v_pk_mul_f32 v[20:21], v[20:21], v[6:7]
	v_mul_f32_e32 v32, v54, v33
	v_pk_fma_f32 v[22:23], v[22:23], v[14:15], v[20:21]
	v_pk_fma_f32 v[20:21], v[26:27], v[12:13], v[24:25]
	v_mul_f32_e32 v24, v52, v33
	v_fract_f32_e32 v25, v24
	v_cos_f32_e32 v24, v25
	v_sin_f32_e32 v26, v25
	v_mul_f32_e32 v25, v53, v33
	v_mul_f32_e32 v33, v55, v33
	v_fract_f32_e32 v27, v25
	v_fract_f32_e32 v34, v32
	v_fract_f32_e32 v35, v33
	v_cos_f32_e32 v25, v27
	v_cos_f32_e32 v32, v34
	v_sin_f32_e32 v34, v34
	v_cos_f32_e32 v33, v35
	v_sin_f32_e32 v35, v35
	v_sin_f32_e32 v27, v27
	v_pk_mul_f32 v[52:53], v[188:189], v[24:25] op_sel_hi:[0,1]
	v_pk_mul_f32 v[32:33], v[188:189], v[32:33] op_sel_hi:[0,1]
	v_pk_mul_f32 v[34:35], v[188:189], v[34:35] op_sel_hi:[0,1]
	v_pk_mul_f32 v[54:55], v[188:189], v[26:27] op_sel_hi:[0,1]
	v_pk_mul_f32 v[24:25], v[54:55], v[0:1]
	v_pk_mul_f32 v[26:27], v[34:35], v[2:3]
	v_pk_fma_f32 v[24:25], v[52:53], v[8:9], v[24:25] neg_lo:[0,0,1] neg_hi:[0,0,1]
	v_pk_fma_f32 v[26:27], v[32:33], v[10:11], v[26:27] neg_lo:[0,0,1] neg_hi:[0,0,1]
	v_pk_mul_f32 v[52:53], v[52:53], v[0:1]
	v_pk_mul_f32 v[32:33], v[32:33], v[2:3]
	s_nop 0
	v_pk_fma_f32 v[34:35], v[34:35], v[10:11], v[32:33]
	v_pk_fma_f32 v[32:33], v[54:55], v[8:9], v[52:53]
	s_cbranch_vccnz .LBB0_752
	v_pk_mul_f32 v[52:53], v[18:19], v[18:19]
	v_pk_mul_f32 v[54:55], v[16:17], v[16:17]
	s_nop 0
	v_pk_mov_b32 v[60:61], v[54:55], v[52:53] op_sel:[1,0]
	v_mov_b32_e32 v55, v53
	v_pk_add_f32 v[52:53], v[60:61], v[54:55]
	v_pk_mul_f32 v[54:55], v[26:27], v[26:27]
	v_pk_add_f32 v[52:53], v[52:53], v[52:53] op_sel_hi:[0,1]
	v_pk_mul_f32 v[60:61], v[24:25], v[24:25]
	v_mul_f32_e32 v52, v20, v20
	v_pk_mov_b32 v[62:63], v[60:61], v[54:55] op_sel:[1,0]
	v_mov_b32_e32 v61, v55
	v_pk_add_f32 v[54:55], v[62:63], v[60:61]
	v_pk_fma_f32 v[60:61], v[20:21], v[20:21], v[52:53] op_sel_hi:[1,1,0]
	v_mul_f32_e32 v52, v22, v22
	v_pk_add_f32 v[54:55], v[54:55], v[54:55] op_sel_hi:[0,1]
	v_pk_fma_f32 v[62:63], v[22:23], v[22:23], v[52:53] op_sel_hi:[1,1,0]
	v_mul_f32_e32 v60, v32, v32
	v_mul_f32_e32 v62, v33, v33
	v_mul_f32_e32 v52, v34, v34
	v_mul_f32_e32 v54, v35, v35
	v_pk_add_f32 v[60:61], v[60:61], v[62:63]
	v_pk_add_f32 v[52:53], v[52:53], v[54:55]
	v_and_b32_e32 v54, 64, v207
	v_pk_add_f32 v[52:53], v[60:61], v[52:53]
	v_add_u32_e32 v54, 64, v54
	v_add_f32_e32 v52, v52, v53
	v_xor_b32_e32 v53, 16, v207
	v_cmp_lt_i32_e32 vcc, v53, v54
	s_nop 1
	v_cndmask_b32_e32 v53, v207, v53, vcc
	v_lshlrev_b32_e32 v53, 2, v53
	ds_bpermute_b32 v53, v53, v52
	s_waitcnt lgkmcnt(0)
	v_add_f32_e32 v52, v52, v53
	v_xor_b32_e32 v53, 32, v207
	v_cmp_lt_i32_e32 vcc, v53, v54
	s_nop 1
	v_cndmask_b32_e32 v53, v207, v53, vcc
	v_lshlrev_b32_e32 v53, 2, v53
	ds_bpermute_b32 v53, v53, v52
	s_waitcnt lgkmcnt(0)
	v_add_f32_e32 v52, v52, v53
	v_max_f32_e32 v53, v74, v74
	v_max_f32_e32 v59, v53, v52

; __device__ __forceinline__ unsigned cvt_pk_bf16(float lo, float hi) { unsigned r; asm volatile("v_cvt_pk_bf16_f32 %0, %1, %2" : "=v"(r) : "v"(lo), "v"(hi)); return r; }
;     __device__ __forceinline__ void operator()(const f32x4 (&acc)[2][2][4][2], const Unit& u, int wr, int wc, int fr, int fq, PG8_LAS unsigned char* lds) const {
;     ...
;                 bf16_t* rowp = P + ((size_t)slot * 81920 + row) * 64 + (((fq & 1) << 4) + ((fq >> 1) << 3));
; #pragma unroll
;                 for (int bj = 0; bj < 2; ++bj) {
;                     unsigned a0 = cvt_pk_bf16(v[bj][0][0], v[bj][0][1]), a1 = cvt_pk_bf16(v[bj][0][2], v[bj][0][3]), b0 = cvt_pk_bf16(v[bj][1][0], v[bj][1][1]), b1 = cvt_pk_bf16(v[bj][1][2], v[bj][1][3]);
;                     { auto r = __builtin_amdgcn_permlane16_swap(a0, b0, false, false); a0 = r[0]; b0 = r[1]; }
;                     { auto r = __builtin_amdgcn_permlane16_swap(a1, b1, false, false); a1 = r[0]; b1 = r[1]; }
;                     u32x4 w; w.x = a0; w.y = a1; w.z = b0; w.w = b1; *(u32x4*)(rowp + 32 * bj) = w; }
;             }
;         if (type == 4) {
; #pragma unroll
;             for (int o = 1; o < 16; o <<= 1) kmx = __builtin_fmaxf(kmx, __shfl_xor(kmx, o));
;             const int r0 = u.pm * BM; const int seq = r0 < TPROMPT ? (r0 >> 11) : 32 + ((r0 - TPROMPT) >> 12);
;             if (fr == 0 && fq == 0) atomicMax(kmax + seq * 8 + (slot - 20), __float_as_uint(kmx));
.LBB0_755:
	v_lshl_add_u64 v[0:1], s[80:81], 0, v[56:57]
	v_lshlrev_b64 v[0:1], 7, v[0:1]
	v_lshl_add_u64 v[4:5], v[176:177], 0, v[0:1]
	v_cvt_pk_bf16_f32 v0, v16, v17
	v_cvt_pk_bf16_f32 v1, v18, v19
	v_cvt_pk_bf16_f32 v2, v24, v25
	v_cvt_pk_bf16_f32 v3, v26, v27
	s_and_b64 vcc, exec, s[78:79]
	v_permlane16_swap_b32_e32 v0, v2
	v_permlane16_swap_b32_e32 v1, v3
	global_store_dwordx4 v[4:5], v[0:3], off nt
	s_nop 1
	v_cvt_pk_bf16_f32 v0, v20, v21
	v_cvt_pk_bf16_f32 v1, v22, v23
	v_cvt_pk_bf16_f32 v2, v32, v33
	v_cvt_pk_bf16_f32 v3, v34, v35
	s_nop 0
	v_permlane16_swap_b32_e32 v0, v2
	v_permlane16_swap_b32_e32 v1, v3
	global_store_dwordx4 v[4:5], v[0:3], off offset:64 nt
	s_cbranch_vccz .LBB0_762
	s_nop 0
	v_and_b32_e32 v0, 64, v207
	v_add_u32_e32 v1, 64, v0
	v_xor_b32_e32 v0, 1, v207
	v_cmp_lt_i32_e32 vcc, v0, v1
	v_xor_b32_e32 v3, 2, v207
	v_max_f32_e32 v2, v59, v59
	v_cndmask_b32_e32 v0, v207, v0, vcc
	v_lshlrev_b32_e32 v0, 2, v0
	ds_bpermute_b32 v0, v0, v59
	v_cmp_lt_i32_e32 vcc, v3, v1
	s_waitcnt lgkmcnt(0)
	v_max_f32_e32 v0, v0, v0
	v_max_f32_e32 v0, v2, v0
	v_cndmask_b32_e32 v2, v207, v3, vcc
	v_lshlrev_b32_e32 v2, 2, v2
	ds_bpermute_b32 v2, v2, v0
	v_xor_b32_e32 v3, 4, v207
	v_cmp_lt_i32_e32 vcc, v3, v1
	s_waitcnt lgkmcnt(0)
	v_max_f32_e32 v2, v2, v2
	v_max_f32_e32 v0, v0, v2
	v_cndmask_b32_e32 v2, v207, v3, vcc
	v_lshlrev_b32_e32 v2, 2, v2
	ds_bpermute_b32 v2, v2, v0
	v_xor_b32_e32 v3, 8, v207
	v_cmp_lt_i32_e32 vcc, v3, v1
	s_waitcnt lgkmcnt(0)
	v_max_f32_e32 v2, v2, v2
	v_cndmask_b32_e32 v1, v207, v3, vcc
	v_max_f32_e32 v0, v0, v2
	v_lshlrev_b32_e32 v1, 2, v1
	ds_bpermute_b32 v1, v1, v0
	s_and_saveexec_b64 s[8:9], s[4:5]
	s_cbranch_execz .LBB0_761
	s_waitcnt lgkmcnt(0)
	v_max_f32_e32 v1, v1, v1
	v_max_f32_e32 v0, v0, v0
	s_mov_b64 s[10:11], exec
	s_ashr_i32 s75, s74, 31
	v_max_f32_e32 v0, v0, v1
	s_mov_b32 s12, 0
